# RG-LRU conv with v_pk_fma_f32, two channel groups interleaved (four independent FMA chains), same tap order
# speedup vs baseline: 1.0084x; 1.0022x over previous
; #define LAS __attribute__((address_space(3)))
; __device__ __forceinline__ unsigned pk2(float lo, float hi) { f32x2_t v = {lo, hi}; bf16x2_t b = __builtin_convertvector(v, bf16x2_t); return __builtin_bit_cast(unsigned, b); }
; __device__ __forceinline__ float bflo(unsigned u) { return __uint_as_float(u << 16); }
; __device__ __forceinline__ float bfhi(unsigned u) { return __uint_as_float(u & 0xffff0000u); }
; __device__ __forceinline__ void lru_phase(const Ptrs& P, LAS unsigned char* lds, int G, int wave, int lane, int tid) {
;     ...
;         float xc[5][2][4]; bf16x8 xf[5];
;         {
;           __builtin_amdgcn_sched_barrier(0);
; #pragma unroll
;           for (int s = 0; s < 5; ++s) { unsigned pkd[4];
; #pragma unroll
;               for (int half = 0; half < 2; ++half) { const int ch0 = 16 * s + 8 * half;
;                   const f32x4 cb = *(const LAS f32x4*)(par + 4 * LB + ch0 + 4 * hh);
;                   float a0 = cb[0], a1 = cb[1], a2 = cb[2], a3 = cb[3];
; #pragma unroll
;                   for (int tap = 0; tap < 4; ++tap) { const v2u rw = raw[s * 2 + half][tap];
;                       const f32x4 cw = *(const LAS f32x4*)(par + tap * LB + ch0 + 4 * hh);
;                       float c0 = cw[0], c1 = cw[1], c2 = cw[2], c3 = cw[3]; asm("" : "+v"(c0), "+v"(c1), "+v"(c2), "+v"(c3));
;                       a0 = __builtin_fmaf(c0, bflo(rw.x), a0); a1 = __builtin_fmaf(c1, bfhi(rw.x), a1); a2 = __builtin_fmaf(c2, bflo(rw.y), a2); a3 = __builtin_fmaf(c3, bfhi(rw.y), a3); }
;                   asm volatile("" : "+v"(a0), "+v"(a1), "+v"(a2), "+v"(a3));
;                   xc[s][half][0] = a0; xc[s][half][1] = a1; xc[s][half][2] = a2; xc[s][half][3] = a3;
;                   pkd[2 * half] = pk2(a0, a1); pkd[2 * half + 1] = pk2(a2, a3); __builtin_amdgcn_sched_barrier(0); }
;               v4u t = {pkd[0], pkd[1], pkd[2], pkd[3]}; xf[s] = __builtin_bit_cast(bf16x8, t); __builtin_amdgcn_sched_barrier(0); } }
.LBB0_308:
	s_ashr_i32 s35, s20, 6
	s_lshl_b32 s34, s35, 8
	s_bfe_u32 s31, s20, 0x20004
	s_add_i32 s34, s34, s26
	ds_read_b128 v[204:207], v234 offset:38144
	ds_read_b128 v[188:191], v234 offset:36864
	ds_read_b128 v[192:195], v234 offset:37184
	ds_read_b128 v[196:199], v234 offset:37504
	ds_read_b128 v[200:203], v234 offset:37824
	ds_read_b128 v[224:227], v234 offset:38176
	ds_read_b128 v[208:211], v234 offset:36896
	ds_read_b128 v[212:215], v234 offset:37216
	ds_read_b128 v[216:219], v234 offset:37536
	ds_read_b128 v[220:223], v234 offset:37856
	s_waitcnt vmcnt(33)
	v_lshlrev_b32_e32 v8, 16, v36
	v_and_b32_e32 v9, 0xffff0000, v36
	v_lshlrev_b32_e32 v10, 16, v37
	v_and_b32_e32 v11, 0xffff0000, v37
	v_lshlrev_b32_e32 v176, 16, v38
	v_and_b32_e32 v177, 0xffff0000, v38
	v_lshlrev_b32_e32 v178, 16, v39
	v_and_b32_e32 v179, 0xffff0000, v39
	s_waitcnt lgkmcnt(8)
	v_pk_fma_f32 v[228:229], v[188:189], v[8:9], v[204:205]
	v_pk_fma_f32 v[230:231], v[190:191], v[10:11], v[206:207]
	s_waitcnt lgkmcnt(3)
	v_pk_fma_f32 v[252:253], v[208:209], v[176:177], v[224:225]
	v_pk_fma_f32 v[254:255], v[210:211], v[178:179], v[226:227]
	s_waitcnt vmcnt(23)
	v_lshlrev_b32_e32 v12, 16, v168
	v_and_b32_e32 v13, 0xffff0000, v168
	v_lshlrev_b32_e32 v14, 16, v169
	v_and_b32_e32 v15, 0xffff0000, v169
	v_lshlrev_b32_e32 v180, 16, v164
	v_and_b32_e32 v181, 0xffff0000, v164
	v_lshlrev_b32_e32 v182, 16, v165
	v_and_b32_e32 v183, 0xffff0000, v165
	s_waitcnt lgkmcnt(7)
	v_pk_fma_f32 v[228:229], v[192:193], v[12:13], v[228:229]
	v_pk_fma_f32 v[230:231], v[194:195], v[14:15], v[230:231]
	s_waitcnt lgkmcnt(2)
	v_pk_fma_f32 v[252:253], v[212:213], v[180:181], v[252:253]
	v_pk_fma_f32 v[254:255], v[214:215], v[182:183], v[254:255]
	s_waitcnt vmcnt(13)
	v_lshlrev_b32_e32 v8, 16, v172
	v_and_b32_e32 v9, 0xffff0000, v172
	v_lshlrev_b32_e32 v10, 16, v173
	v_and_b32_e32 v11, 0xffff0000, v173
	v_lshlrev_b32_e32 v176, 16, v166
	v_and_b32_e32 v177, 0xffff0000, v166
	v_lshlrev_b32_e32 v178, 16, v167
	v_and_b32_e32 v179, 0xffff0000, v167
	s_waitcnt lgkmcnt(6)
	v_pk_fma_f32 v[228:229], v[196:197], v[8:9], v[228:229]
	v_pk_fma_f32 v[230:231], v[198:199], v[10:11], v[230:231]
	s_waitcnt lgkmcnt(1)
	v_pk_fma_f32 v[252:253], v[216:217], v[176:177], v[252:253]
	v_pk_fma_f32 v[254:255], v[218:219], v[178:179], v[254:255]
	s_waitcnt vmcnt(3)
	v_lshlrev_b32_e32 v12, 16, v174
	v_and_b32_e32 v13, 0xffff0000, v174
	v_lshlrev_b32_e32 v14, 16, v175
	v_and_b32_e32 v15, 0xffff0000, v175
	s_waitcnt vmcnt(2)
	v_lshlrev_b32_e32 v180, 16, v170
	v_and_b32_e32 v181, 0xffff0000, v170
	v_lshlrev_b32_e32 v182, 16, v171
	v_and_b32_e32 v183, 0xffff0000, v171
	s_waitcnt lgkmcnt(5)
	v_pk_fma_f32 v[228:229], v[200:201], v[12:13], v[228:229]
	v_pk_fma_f32 v[50:51], v[202:203], v[14:15], v[230:231]
	s_waitcnt lgkmcnt(0)
	v_pk_fma_f32 v[252:253], v[220:221], v[180:181], v[252:253]
	v_pk_fma_f32 v[58:59], v[222:223], v[182:183], v[254:255]
	v_mov_b32_e32 v45, v228
	v_mov_b32_e32 v46, v229
	v_cvt_pk_bf16_f32 v36, v228, v229
	v_cvt_pk_bf16_f32 v37, v50, v51
	v_mov_b32_e32 v53, v252
	v_mov_b32_e32 v54, v253
	v_cvt_pk_bf16_f32 v38, v252, v253
	v_cvt_pk_bf16_f32 v39, v58, v59
	ds_read_b128 v[204:207], v234 offset:38208
	ds_read_b128 v[188:191], v234 offset:36928
	ds_read_b128 v[192:195], v234 offset:37248
	ds_read_b128 v[196:199], v234 offset:37568
	ds_read_b128 v[200:203], v234 offset:37888
	ds_read_b128 v[224:227], v234 offset:38240
	ds_read_b128 v[208:211], v234 offset:36960
	ds_read_b128 v[212:215], v234 offset:37280
	ds_read_b128 v[216:219], v234 offset:37600
	ds_read_b128 v[220:223], v234 offset:37920
	v_lshlrev_b32_e32 v8, 16, v40
	v_and_b32_e32 v9, 0xffff0000, v40
	v_lshlrev_b32_e32 v10, 16, v41
	v_and_b32_e32 v11, 0xffff0000, v41
	v_lshlrev_b32_e32 v176, 16, v42
	v_and_b32_e32 v177, 0xffff0000, v42
	v_lshlrev_b32_e32 v178, 16, v43
	v_and_b32_e32 v179, 0xffff0000, v43
	s_waitcnt lgkmcnt(8)
	v_pk_fma_f32 v[228:229], v[188:189], v[8:9], v[204:205]
	v_pk_fma_f32 v[230:231], v[190:191], v[10:11], v[206:207]
	s_waitcnt lgkmcnt(3)
	v_pk_fma_f32 v[252:253], v[208:209], v[176:177], v[224:225]
	v_pk_fma_f32 v[254:255], v[210:211], v[178:179], v[226:227]
	v_lshlrev_b32_e32 v12, 16, v156
	v_and_b32_e32 v13, 0xffff0000, v156
	v_lshlrev_b32_e32 v14, 16, v157
	v_and_b32_e32 v15, 0xffff0000, v157
	v_lshlrev_b32_e32 v180, 16, v150
	v_and_b32_e32 v181, 0xffff0000, v150
	v_lshlrev_b32_e32 v182, 16, v151
	v_and_b32_e32 v183, 0xffff0000, v151
	s_waitcnt lgkmcnt(7)
	v_pk_fma_f32 v[228:229], v[192:193], v[12:13], v[228:229]
	v_pk_fma_f32 v[230:231], v[194:195], v[14:15], v[230:231]
	s_waitcnt lgkmcnt(2)
	v_pk_fma_f32 v[252:253], v[212:213], v[180:181], v[252:253]
	v_pk_fma_f32 v[254:255], v[214:215], v[182:183], v[254:255]
	v_lshlrev_b32_e32 v8, 16, v160
	v_and_b32_e32 v9, 0xffff0000, v160
	v_lshlrev_b32_e32 v10, 16, v161
	v_and_b32_e32 v11, 0xffff0000, v161
	v_lshlrev_b32_e32 v176, 16, v154
	v_and_b32_e32 v177, 0xffff0000, v154
	v_lshlrev_b32_e32 v178, 16, v155
	v_and_b32_e32 v179, 0xffff0000, v155
	s_waitcnt lgkmcnt(6)
	v_pk_fma_f32 v[228:229], v[196:197], v[8:9], v[228:229]
	v_pk_fma_f32 v[230:231], v[198:199], v[10:11], v[230:231]
	s_waitcnt lgkmcnt(1)
	v_pk_fma_f32 v[252:253], v[216:217], v[176:177], v[252:253]
	v_pk_fma_f32 v[254:255], v[218:219], v[178:179], v[254:255]
	v_lshlrev_b32_e32 v12, 16, v162
	v_and_b32_e32 v13, 0xffff0000, v162
	v_lshlrev_b32_e32 v14, 16, v163
	v_and_b32_e32 v15, 0xffff0000, v163
	v_lshlrev_b32_e32 v180, 16, v158
	v_and_b32_e32 v181, 0xffff0000, v158
	v_lshlrev_b32_e32 v182, 16, v159
	v_and_b32_e32 v183, 0xffff0000, v159
	s_waitcnt lgkmcnt(5)
; #define LAS __attribute__((address_space(3)))
; __device__ __forceinline__ unsigned pk2(float lo, float hi) { f32x2_t v = {lo, hi}; bf16x2_t b = __builtin_convertvector(v, bf16x2_t); return __builtin_bit_cast(unsigned, b); }
; __device__ __forceinline__ float bflo(unsigned u) { return __uint_as_float(u << 16); }
; __device__ __forceinline__ float bfhi(unsigned u) { return __uint_as_float(u & 0xffff0000u); }
; __device__ __forceinline__ void lru_phase(const Ptrs& P, LAS unsigned char* lds, int G, int wave, int lane, int tid) {
;     ...
;         float xc[5][2][4]; bf16x8 xf[5];
;         {
;           __builtin_amdgcn_sched_barrier(0);
; #pragma unroll
;           for (int s = 0; s < 5; ++s) { unsigned pkd[4];
; #pragma unroll
;               for (int half = 0; half < 2; ++half) { const int ch0 = 16 * s + 8 * half;
;                   const f32x4 cb = *(const LAS f32x4*)(par + 4 * LB + ch0 + 4 * hh);
;                   float a0 = cb[0], a1 = cb[1], a2 = cb[2], a3 = cb[3];
; #pragma unroll
;                   for (int tap = 0; tap < 4; ++tap) { const v2u rw = raw[s * 2 + half][tap];
;                       const f32x4 cw = *(const LAS f32x4*)(par + tap * LB + ch0 + 4 * hh);
;                       float c0 = cw[0], c1 = cw[1], c2 = cw[2], c3 = cw[3]; asm("" : "+v"(c0), "+v"(c1), "+v"(c2), "+v"(c3));
;                       a0 = __builtin_fmaf(c0, bflo(rw.x), a0); a1 = __builtin_fmaf(c1, bfhi(rw.x), a1); a2 = __builtin_fmaf(c2, bflo(rw.y), a2); a3 = __builtin_fmaf(c3, bfhi(rw.y), a3); }
;                   asm volatile("" : "+v"(a0), "+v"(a1), "+v"(a2), "+v"(a3));
;                   xc[s][half][0] = a0; xc[s][half][1] = a1; xc[s][half][2] = a2; xc[s][half][3] = a3;
;                   pkd[2 * half] = pk2(a0, a1); pkd[2 * half + 1] = pk2(a2, a3); __builtin_amdgcn_sched_barrier(0); }
;               v4u t = {pkd[0], pkd[1], pkd[2], pkd[3]}; xf[s] = __builtin_bit_cast(bf16x8, t); __builtin_amdgcn_sched_barrier(0); } }
	v_pk_fma_f32 v[228:229], v[200:201], v[12:13], v[228:229]
	v_pk_fma_f32 v[66:67], v[202:203], v[14:15], v[230:231]
	s_waitcnt lgkmcnt(0)
	v_pk_fma_f32 v[252:253], v[220:221], v[180:181], v[252:253]
	v_pk_fma_f32 v[74:75], v[222:223], v[182:183], v[254:255]
	v_mov_b32_e32 v61, v228
	v_mov_b32_e32 v62, v229
	v_cvt_pk_bf16_f32 v40, v228, v229
	v_cvt_pk_bf16_f32 v41, v66, v67
	v_mov_b32_e32 v69, v252
	v_mov_b32_e32 v70, v253
	v_cvt_pk_bf16_f32 v42, v252, v253
	v_cvt_pk_bf16_f32 v43, v74, v75
	ds_read_b128 v[204:207], v234 offset:38272
	ds_read_b128 v[188:191], v234 offset:36992
	ds_read_b128 v[192:195], v234 offset:37312
	ds_read_b128 v[196:199], v234 offset:37632
	ds_read_b128 v[200:203], v234 offset:37952
	ds_read_b128 v[224:227], v234 offset:38304
	ds_read_b128 v[208:211], v234 offset:37024
	ds_read_b128 v[212:215], v234 offset:37344
	ds_read_b128 v[216:219], v234 offset:37664
	ds_read_b128 v[220:223], v234 offset:37984
	v_lshlrev_b32_e32 v8, 16, v76
	v_and_b32_e32 v9, 0xffff0000, v76
	v_lshlrev_b32_e32 v10, 16, v77
	v_and_b32_e32 v11, 0xffff0000, v77
	v_lshlrev_b32_e32 v176, 16, v78
	v_and_b32_e32 v177, 0xffff0000, v78
	v_lshlrev_b32_e32 v178, 16, v79
	v_and_b32_e32 v179, 0xffff0000, v79
	s_waitcnt lgkmcnt(8)
	v_pk_fma_f32 v[228:229], v[188:189], v[8:9], v[204:205]
	v_pk_fma_f32 v[230:231], v[190:191], v[10:11], v[206:207]
	s_waitcnt lgkmcnt(3)
	v_pk_fma_f32 v[252:253], v[208:209], v[176:177], v[224:225]
	v_pk_fma_f32 v[254:255], v[210:211], v[178:179], v[226:227]
	v_lshlrev_b32_e32 v12, 16, v144
	v_and_b32_e32 v13, 0xffff0000, v144
	v_lshlrev_b32_e32 v14, 16, v145
	v_and_b32_e32 v15, 0xffff0000, v145
	v_lshlrev_b32_e32 v180, 16, v126
	v_and_b32_e32 v181, 0xffff0000, v126
	v_lshlrev_b32_e32 v182, 16, v127
	v_and_b32_e32 v183, 0xffff0000, v127
	s_waitcnt lgkmcnt(7)
	v_pk_fma_f32 v[228:229], v[192:193], v[12:13], v[228:229]
	v_pk_fma_f32 v[230:231], v[194:195], v[14:15], v[230:231]
	s_waitcnt lgkmcnt(2)
	v_pk_fma_f32 v[252:253], v[212:213], v[180:181], v[252:253]
	v_pk_fma_f32 v[254:255], v[214:215], v[182:183], v[254:255]
	v_lshlrev_b32_e32 v8, 16, v148
	v_and_b32_e32 v9, 0xffff0000, v148
	v_lshlrev_b32_e32 v10, 16, v149
	v_and_b32_e32 v11, 0xffff0000, v149
	v_lshlrev_b32_e32 v176, 16, v142
	v_and_b32_e32 v177, 0xffff0000, v142
	v_lshlrev_b32_e32 v178, 16, v143
	v_and_b32_e32 v179, 0xffff0000, v143
	s_waitcnt lgkmcnt(6)
	v_pk_fma_f32 v[228:229], v[196:197], v[8:9], v[228:229]
	v_pk_fma_f32 v[230:231], v[198:199], v[10:11], v[230:231]
	s_waitcnt lgkmcnt(1)
	v_pk_fma_f32 v[252:253], v[216:217], v[176:177], v[252:253]
	v_pk_fma_f32 v[254:255], v[218:219], v[178:179], v[254:255]
	v_lshlrev_b32_e32 v12, 16, v152
	v_and_b32_e32 v13, 0xffff0000, v152
	v_lshlrev_b32_e32 v14, 16, v153
	v_and_b32_e32 v15, 0xffff0000, v153
	v_lshlrev_b32_e32 v180, 16, v146
	v_and_b32_e32 v181, 0xffff0000, v146
	v_lshlrev_b32_e32 v182, 16, v147
	v_and_b32_e32 v183, 0xffff0000, v147
	s_waitcnt lgkmcnt(5)
	v_pk_fma_f32 v[228:229], v[200:201], v[12:13], v[228:229]
	v_pk_fma_f32 v[86:87], v[202:203], v[14:15], v[230:231]
	s_waitcnt lgkmcnt(0)
	v_pk_fma_f32 v[252:253], v[220:221], v[180:181], v[252:253]
	v_pk_fma_f32 v[94:95], v[222:223], v[182:183], v[254:255]
	v_mov_b32_e32 v81, v228
	v_mov_b32_e32 v82, v229
	v_cvt_pk_bf16_f32 v76, v228, v229
	v_cvt_pk_bf16_f32 v77, v86, v87
	v_mov_b32_e32 v89, v252
	v_mov_b32_e32 v90, v253
	v_cvt_pk_bf16_f32 v78, v252, v253
	v_cvt_pk_bf16_f32 v79, v94, v95
	ds_read_b128 v[204:207], v234 offset:38336
	ds_read_b128 v[188:191], v234 offset:37056
	ds_read_b128 v[192:195], v234 offset:37376
	ds_read_b128 v[196:199], v234 offset:37696
	ds_read_b128 v[200:203], v234 offset:38016
	ds_read_b128 v[224:227], v234 offset:38368
	ds_read_b128 v[208:211], v234 offset:37088
	ds_read_b128 v[212:215], v234 offset:37408
	ds_read_b128 v[216:219], v234 offset:37728
	ds_read_b128 v[220:223], v234 offset:38048
	v_lshlrev_b32_e32 v8, 16, v112
	v_and_b32_e32 v9, 0xffff0000, v112
	v_lshlrev_b32_e32 v10, 16, v113
	v_and_b32_e32 v11, 0xffff0000, v113
	v_lshlrev_b32_e32 v176, 16, v28
	v_and_b32_e32 v177, 0xffff0000, v28
	v_lshlrev_b32_e32 v178, 16, v29
	v_and_b32_e32 v179, 0xffff0000, v29
	s_waitcnt lgkmcnt(8)
	v_pk_fma_f32 v[228:229], v[188:189], v[8:9], v[204:205]
	v_pk_fma_f32 v[230:231], v[190:191], v[10:11], v[206:207]
	s_waitcnt lgkmcnt(3)
	v_pk_fma_f32 v[252:253], v[208:209], v[176:177], v[224:225]
	v_pk_fma_f32 v[254:255], v[210:211], v[178:179], v[226:227]
	v_lshlrev_b32_e32 v12, 16, v118
	v_and_b32_e32 v13, 0xffff0000, v118
	v_lshlrev_b32_e32 v14, 16, v119
	v_and_b32_e32 v15, 0xffff0000, v119
	v_lshlrev_b32_e32 v180, 16, v114
	v_and_b32_e32 v181, 0xffff0000, v114
	v_lshlrev_b32_e32 v182, 16, v115
	v_and_b32_e32 v183, 0xffff0000, v115
	s_waitcnt lgkmcnt(7)
	v_pk_fma_f32 v[228:229], v[192:193], v[12:13], v[228:229]
	v_pk_fma_f32 v[230:231], v[194:195], v[14:15], v[230:231]
	s_waitcnt lgkmcnt(2)
	v_pk_fma_f32 v[252:253], v[212:213], v[180:181], v[252:253]
	v_pk_fma_f32 v[254:255], v[214:215], v[182:183], v[254:255]
	v_lshlrev_b32_e32 v8, 16, v124
	v_and_b32_e32 v9, 0xffff0000, v124
	v_lshlrev_b32_e32 v10, 16, v125
	v_and_b32_e32 v11, 0xffff0000, v125
	v_lshlrev_b32_e32 v176, 16, v116
	v_and_b32_e32 v177, 0xffff0000, v116
	v_lshlrev_b32_e32 v178, 16, v117
	v_and_b32_e32 v179, 0xffff0000, v117
	s_waitcnt lgkmcnt(6)
	v_pk_fma_f32 v[228:229], v[196:197], v[8:9], v[228:229]
	v_pk_fma_f32 v[230:231], v[198:199], v[10:11], v[230:231]
	s_waitcnt lgkmcnt(1)
; #define LAS __attribute__((address_space(3)))
; __device__ __forceinline__ unsigned pk2(float lo, float hi) { f32x2_t v = {lo, hi}; bf16x2_t b = __builtin_convertvector(v, bf16x2_t); return __builtin_bit_cast(unsigned, b); }
; __device__ __forceinline__ float bflo(unsigned u) { return __uint_as_float(u << 16); }
; __device__ __forceinline__ void lru_phase(const Ptrs& P, LAS unsigned char* lds, int G, int wave, int lane, int tid) {
;     ...
;           for (int s = 0; s < 5; ++s) { unsigned pkd[4];
; #pragma unroll
;               for (int half = 0; half < 2; ++half) { const int ch0 = 16 * s + 8 * half;
;                   const f32x4 cb = *(const LAS f32x4*)(par + 4 * LB + ch0 + 4 * hh);
;                   float a0 = cb[0], a1 = cb[1], a2 = cb[2], a3 = cb[3];
; #pragma unroll
;                   for (int tap = 0; tap < 4; ++tap) { const v2u rw = raw[s * 2 + half][tap];
;                       const f32x4 cw = *(const LAS f32x4*)(par + tap * LB + ch0 + 4 * hh);
;                       float c0 = cw[0], c1 = cw[1], c2 = cw[2], c3 = cw[3]; asm("" : "+v"(c0), "+v"(c1), "+v"(c2), "+v"(c3));
;                       a0 = __builtin_fmaf(c0, bflo(rw.x), a0); a1 = __builtin_fmaf(c1, bfhi(rw.x), a1); a2 = __builtin_fmaf(c2, bflo(rw.y), a2); a3 = __builtin_fmaf(c3, bfhi(rw.y), a3); }
;                   asm volatile("" : "+v"(a0), "+v"(a1), "+v"(a2), "+v"(a3));
;                   xc[s][half][0] = a0; xc[s][half][1] = a1; xc[s][half][2] = a2; xc[s][half][3] = a3;
;                   pkd[2 * half] = pk2(a0, a1); pkd[2 * half + 1] = pk2(a2, a3); __builtin_amdgcn_sched_barrier(0); }
;               v4u t = {pkd[0], pkd[1], pkd[2], pkd[3]}; xf[s] = __builtin_bit_cast(bf16x8, t); __builtin_amdgcn_sched_barrier(0); } }
;     ...
;         for (int mt = 0; mt < 3; ++mt) {
;             f32x16 gr, gi;
; #pragma unroll
;             for (int i = 0; i < 16; ++i) { gr[i] = 0.f; gi[i] = 0.f; }
;             const LAS bf16x8* wa = (const LAS bf16x8*)(lds + L_WGF) + (size_t)(mt * 6) * 64 + lane;
;             const LAS bf16x8* wb = (const LAS bf16x8*)(lds + L_WGF) + (size_t)((3 + mt) * 6) * 64 + lane;
; #pragma unroll
;             for (int s = 0; s < 5; ++s) { gr = MFMA32(wa[s * 64], xf[s], gr); gi = MFMA32(wb[s * 64], xf[s], gi); }
;             gr = MFMA32(wa[5 * 64], xone, gr); gi = MFMA32(wb[5 * 64], xone, gi);
	v_pk_fma_f32 v[252:253], v[216:217], v[176:177], v[252:253]
	v_pk_fma_f32 v[254:255], v[218:219], v[178:179], v[254:255]
	v_lshlrev_b32_e32 v12, 16, v140
	v_and_b32_e32 v13, 0xffff0000, v140
	v_lshlrev_b32_e32 v14, 16, v141
	v_and_b32_e32 v15, 0xffff0000, v141
	v_lshlrev_b32_e32 v180, 16, v122
	v_and_b32_e32 v181, 0xffff0000, v122
	v_lshlrev_b32_e32 v182, 16, v123
	v_and_b32_e32 v183, 0xffff0000, v123
	s_waitcnt lgkmcnt(5)
	v_pk_fma_f32 v[228:229], v[200:201], v[12:13], v[228:229]
	v_pk_fma_f32 v[102:103], v[202:203], v[14:15], v[230:231]
	s_waitcnt lgkmcnt(0)
	v_pk_fma_f32 v[252:253], v[220:221], v[180:181], v[252:253]
	v_pk_fma_f32 v[110:111], v[222:223], v[182:183], v[254:255]
	v_mov_b32_e32 v97, v228
	v_mov_b32_e32 v98, v229
	v_cvt_pk_bf16_f32 v112, v228, v229
	v_cvt_pk_bf16_f32 v113, v102, v103
	v_mov_b32_e32 v105, v252
	v_mov_b32_e32 v106, v253
	v_cvt_pk_bf16_f32 v114, v252, v253
	v_cvt_pk_bf16_f32 v115, v110, v111
	ds_read_b128 v[204:207], v234 offset:38400
	ds_read_b128 v[188:191], v234 offset:37120
	ds_read_b128 v[192:195], v234 offset:37440
	ds_read_b128 v[196:199], v234 offset:37760
	ds_read_b128 v[200:203], v234 offset:38080
	ds_read_b128 v[224:227], v234 offset:38432
	ds_read_b128 v[208:211], v234 offset:37152
	ds_read_b128 v[212:215], v234 offset:37472
	ds_read_b128 v[216:219], v234 offset:37792
	ds_read_b128 v[220:223], v234 offset:38112
	v_lshlrev_b32_e32 v8, 16, v20
	v_and_b32_e32 v9, 0xffff0000, v20
	v_lshlrev_b32_e32 v10, 16, v21
	v_and_b32_e32 v11, 0xffff0000, v21
	v_lshlrev_b32_e32 v176, 16, v16
	v_and_b32_e32 v177, 0xffff0000, v16
	v_lshlrev_b32_e32 v178, 16, v17
	v_and_b32_e32 v179, 0xffff0000, v17
	s_waitcnt lgkmcnt(8)
	v_pk_fma_f32 v[228:229], v[188:189], v[8:9], v[204:205]
	v_pk_fma_f32 v[230:231], v[190:191], v[10:11], v[206:207]
	s_waitcnt lgkmcnt(3)
	v_pk_fma_f32 v[252:253], v[208:209], v[176:177], v[224:225]
	v_pk_fma_f32 v[254:255], v[210:211], v[178:179], v[226:227]
	v_lshlrev_b32_e32 v12, 16, v24
	v_and_b32_e32 v13, 0xffff0000, v24
	v_lshlrev_b32_e32 v14, 16, v25
	v_and_b32_e32 v15, 0xffff0000, v25
	v_lshlrev_b32_e32 v180, 16, v18
	v_and_b32_e32 v181, 0xffff0000, v18
	v_lshlrev_b32_e32 v182, 16, v19
	v_and_b32_e32 v183, 0xffff0000, v19
	s_waitcnt lgkmcnt(7)
	v_pk_fma_f32 v[228:229], v[192:193], v[12:13], v[228:229]
	v_pk_fma_f32 v[230:231], v[194:195], v[14:15], v[230:231]
	s_waitcnt lgkmcnt(2)
	v_pk_fma_f32 v[252:253], v[212:213], v[180:181], v[252:253]
	v_pk_fma_f32 v[254:255], v[214:215], v[182:183], v[254:255]
	v_lshlrev_b32_e32 v8, 16, v30
	v_and_b32_e32 v9, 0xffff0000, v30
	v_lshlrev_b32_e32 v10, 16, v31
	v_and_b32_e32 v11, 0xffff0000, v31
	v_lshlrev_b32_e32 v176, 16, v22
	v_and_b32_e32 v177, 0xffff0000, v22
	v_lshlrev_b32_e32 v178, 16, v23
	v_and_b32_e32 v179, 0xffff0000, v23
	s_waitcnt lgkmcnt(6)
	v_pk_fma_f32 v[228:229], v[196:197], v[8:9], v[228:229]
	v_pk_fma_f32 v[230:231], v[198:199], v[10:11], v[230:231]
	s_waitcnt lgkmcnt(1)
	v_pk_fma_f32 v[252:253], v[216:217], v[176:177], v[252:253]
	v_pk_fma_f32 v[254:255], v[218:219], v[178:179], v[254:255]
	s_waitcnt vmcnt(1)
	v_lshlrev_b32_e32 v12, 16, v120
	v_and_b32_e32 v13, 0xffff0000, v120
	v_lshlrev_b32_e32 v14, 16, v121
	v_and_b32_e32 v15, 0xffff0000, v121
	s_waitcnt vmcnt(0)
	v_lshlrev_b32_e32 v180, 16, v26
	v_and_b32_e32 v181, 0xffff0000, v26
	v_lshlrev_b32_e32 v182, 16, v27
	v_and_b32_e32 v183, 0xffff0000, v27
	s_waitcnt lgkmcnt(5)
	v_pk_fma_f32 v[228:229], v[200:201], v[12:13], v[228:229]
	v_pk_fma_f32 v[230:231], v[202:203], v[14:15], v[230:231]
	s_waitcnt lgkmcnt(0)
	v_pk_fma_f32 v[252:253], v[220:221], v[180:181], v[252:253]
	v_pk_fma_f32 v[254:255], v[222:223], v[182:183], v[254:255]
	v_mov_b32_e32 v136, v228
	v_mov_b32_e32 v129, v229
	v_mov_b32_e32 v116, v230
	v_mov_b32_e32 v119, v231
	v_cvt_pk_bf16_f32 v124, v228, v229
	v_cvt_pk_bf16_f32 v125, v230, v231
	v_mov_b32_e32 v120, v252
	v_mov_b32_e32 v118, v253
	v_mov_b32_e32 v117, v254
	v_mov_b32_e32 v123, v255
	v_cvt_pk_bf16_f32 v126, v252, v253
	v_cvt_pk_bf16_f32 v127, v254, v255
	ds_read_b128 v[0:3], v237
	ds_read_b128 v[140:143], v237 offset:1024
	ds_read_b128 v[16:19], v237 offset:18432
	ds_read_b128 v[144:147], v237 offset:19456
	s_waitcnt lgkmcnt(3)
	v_mfma_f32_32x32x16_bf16 v[0:15], v[0:3], v[36:39], 0
	s_waitcnt lgkmcnt(1)
	v_mfma_f32_32x32x16_bf16 v[16:31], v[16:19], v[36:39], 0
	v_mfma_f32_32x32x16_bf16 v[0:15], v[140:143], v[40:43], v[0:15]
	s_waitcnt lgkmcnt(0)
	v_mfma_f32_32x32x16_bf16 v[16:31], v[144:147], v[40:43], v[16:31]
	ds_read_b128 v[140:143], v237 offset:2048
	ds_read_b128 v[144:147], v237 offset:3072
	s_waitcnt lgkmcnt(1)
	v_mfma_f32_32x32x16_bf16 v[0:15], v[140:143], v[76:79], v[0:15]
	ds_read_b128 v[140:143], v237 offset:20480
	ds_read_b128 v[148:151], v237 offset:21504
	s_waitcnt lgkmcnt(1)
	v_mfma_f32_32x32x16_bf16 v[16:31], v[140:143], v[76:79], v[16:31]
	v_mfma_f32_32x32x16_bf16 v[0:15], v[144:147], v[112:115], v[0:15]
	ds_read_b128 v[140:143], v237 offset:4096
	ds_read_b128 v[144:147], v237 offset:5120
	s_waitcnt lgkmcnt(2)
	v_mfma_f32_32x32x16_bf16 v[16:31], v[148:151], v[112:115], v[16:31]
	s_waitcnt lgkmcnt(1)
	v_mfma_f32_32x32x16_bf16 v[0:15], v[140:143], v[124:127], v[0:15]
	ds_read_b128 v[140:143], v237 offset:22528
	ds_read_b128 v[148:151], v237 offset:23552
	s_waitcnt lgkmcnt(1)
	v_mfma_f32_32x32x16_bf16 v[16:31], v[140:143], v[124:127], v[16:31]
	v_mfma_f32_32x32x16_bf16 v[0:15], v[144:147], v[32:35], v[0:15]
	s_waitcnt lgkmcnt(0)
; #define LAS __attribute__((address_space(3)))
; __device__ __forceinline__ float ex2(float x) { return __builtin_amdgcn_exp2f(x); }
; __device__ __forceinline__ float rcpf_(float x) { return __builtin_amdgcn_rcpf(x); }
; __device__ __forceinline__ void lru_phase(const Ptrs& P, LAS unsigned char* lds, int G, int wave, int lane, int tid) {
;     ...
; #pragma unroll
;             for (int i4 = 0; i4 < 4; ++i4) { if (mt == 2 && i4 >= 2) continue;
;                 const int s = 2 * mt + (i4 >> 1), half = i4 & 1, ch0 = 16 * s + 8 * half + 4 * hh;
;                 const f32x4 ls2 = *(const LAS f32x4*)(par + 7 * LB + ch0);
;                 float A4[4], B4[4];
; #pragma unroll
;                 for (int q = 0; q < 4; ++q) { const int i = 4 * i4 + q;
;                     const float rg = rcpf_(1.0f + ex2(gr[i])), ig = rcpf_(1.0f + ex2(gi[i]));
;                     const float la2 = ls2[q] * rg, a = ex2(la2), xx = (2.0f * LN2) * la2;
;                     const float poly = -xx * (1.0f + xx * (0.5f + xx * ((1.0f / 6.0f) + xx * ((1.0f / 24.0f) + xx * (1.0f / 120.0f)))));
;                     const float om = (xx > -0.25f) ? poly : (1.0f - a * a);
;                     A4[q] = a; B4[q] = __builtin_amdgcn_sqrtf(om) * (ig * xc[s][half][q]); }
;                 asm volatile("s_nop 1\n\t"
;                     LRU_DPP4("row_shr:1 row_mask:0xf bank_mask:0xf") LRU_DPP4("row_shr:2 row_mask:0xf bank_mask:0xf") LRU_DPP4("row_shr:4 row_mask:0xf bank_mask:0xf")
;                     LRU_DPP4("row_shr:8 row_mask:0xf bank_mask:0xf") LRU_DPP4("row_bcast:15 row_mask:0xa bank_mask:0xf")
;                     : "+v"(A4[0]), "+v"(A4[1]), "+v"(A4[2]), "+v"(A4[3]), "+v"(B4[0]), "+v"(B4[1]), "+v"(B4[2]), "+v"(B4[3]));
; #pragma unroll
;                 for (int q = 0; q < 4; ++q) { Av[s][half][q] = A4[q]; xc[s][half][q] = B4[q]; }
;                 __builtin_amdgcn_sched_barrier(0); }
	v_mfma_f32_32x32x16_bf16 v[16:31], v[148:151], v[32:35], v[16:31]
	s_nop 9
	ds_read_b128 v[140:143], v234 offset:39104
	v_exp_f32_e32 v0, v0
	v_exp_f32_e32 v1, v1
	v_exp_f32_e32 v2, v2
	v_exp_f32_e32 v3, v3
	v_exp_f32_e32 v16, v16
	v_exp_f32_e32 v17, v17
	v_exp_f32_e32 v18, v18
	v_exp_f32_e32 v19, v19
	v_pk_add_f32 v[0:1], v[0:1], v[240:241] op_sel_hi:[1,0]
	v_pk_add_f32 v[2:3], v[2:3], v[240:241] op_sel_hi:[1,0]
	v_pk_add_f32 v[16:17], v[16:17], v[240:241] op_sel_hi:[1,0]
	v_pk_add_f32 v[18:19], v[18:19], v[240:241] op_sel_hi:[1,0]
	v_rcp_f32_e32 v0, v0
	v_rcp_f32_e32 v1, v1
	v_rcp_f32_e32 v2, v2
	v_rcp_f32_e32 v3, v3
	v_rcp_f32_e32 v16, v16
	v_rcp_f32_e32 v17, v17
	v_rcp_f32_e32 v18, v18
	v_rcp_f32_e32 v19, v19
	v_mul_f32_e32 v200, v45, v16
	v_mul_f32_e32 v201, v46, v17
	v_mul_f32_e32 v202, v50, v18
	v_mul_f32_e32 v203, v51, v19
	s_waitcnt lgkmcnt(0)
	v_pk_mul_f32 v[0:1], v[0:1], v[140:141]
	v_pk_mul_f32 v[2:3], v[2:3], v[142:143]
	v_pk_mul_f32 v[204:205], v[0:1], v[242:243] op_sel_hi:[1,0]
	v_pk_mul_f32 v[206:207], v[2:3], v[242:243] op_sel_hi:[1,0]
	v_exp_f32_e32 v44, v0
	v_exp_f32_e32 v45, v1
	v_exp_f32_e32 v46, v2
	v_exp_f32_e32 v47, v3
	v_pk_fma_f32 v[208:209], v[204:205], v[244:245], v[238:239] op_sel_hi:[1,0,0]
	v_pk_fma_f32 v[210:211], v[206:207], v[244:245], v[238:239] op_sel_hi:[1,0,0]
	v_pk_fma_f32 v[208:209], v[204:205], v[208:209], v[246:247] op_sel_hi:[1,1,0]
	v_pk_fma_f32 v[210:211], v[206:207], v[210:211], v[246:247] op_sel_hi:[1,1,0]
	v_pk_fma_f32 v[208:209], v[204:205], v[208:209], v[248:249] op_sel_hi:[1,1,0]
	v_pk_fma_f32 v[210:211], v[206:207], v[210:211], v[248:249] op_sel_hi:[1,1,0]
	v_pk_fma_f32 v[208:209], v[204:205], v[208:209], v[240:241] op_sel_hi:[1,1,0]
	v_pk_fma_f32 v[210:211], v[206:207], v[210:211], v[240:241] op_sel_hi:[1,1,0]
	v_pk_mul_f32 v[208:209], v[208:209], v[204:205] neg_lo:[0,1] neg_hi:[0,1]
	v_pk_mul_f32 v[210:211], v[210:211], v[206:207] neg_lo:[0,1] neg_hi:[0,1]
	v_pk_fma_f32 v[212:213], v[44:45], v[44:45], v[240:241] op_sel_hi:[1,1,0] neg_lo:[1,0,0] neg_hi:[1,0,0]
	v_pk_fma_f32 v[214:215], v[46:47], v[46:47], v[240:241] op_sel_hi:[1,1,0] neg_lo:[1,0,0] neg_hi:[1,0,0]
	v_cmp_lt_f32_e64 s[70:71], s29, v204
	v_cmp_lt_f32_e64 s[72:73], s29, v205
	v_cmp_lt_f32_e64 s[74:75], s29, v206
	v_cmp_lt_f32_e64 s[76:77], s29, v207
	v_cndmask_b32_e64 v212, v212, v208, s[70:71]
	v_cndmask_b32_e64 v213, v213, v209, s[72:73]
	v_cndmask_b32_e64 v214, v214, v210, s[74:75]
	v_cndmask_b32_e64 v215, v215, v211, s[76:77]
	v_sqrt_f32_e32 v212, v212
	v_sqrt_f32_e32 v213, v213
	v_sqrt_f32_e32 v214, v214
	v_sqrt_f32_e32 v215, v215
	v_pk_mul_f32 v[48:49], v[200:201], v[212:213]
	v_pk_mul_f32 v[50:51], v[202:203], v[214:215]
	s_nop 1
	v_fmac_f32_dpp v48, v48, v44 row_shr:1 row_mask:0xf bank_mask:0xf
	v_fmac_f32_dpp v49, v49, v45 row_shr:1 row_mask:0xf bank_mask:0xf
	v_fmac_f32_dpp v50, v50, v46 row_shr:1 row_mask:0xf bank_mask:0xf
	v_fmac_f32_dpp v51, v51, v47 row_shr:1 row_mask:0xf bank_mask:0xf
	v_mul_f32_dpp v44, v44, v44 row_shr:1 row_mask:0xf bank_mask:0xf
	v_mul_f32_dpp v45, v45, v45 row_shr:1 row_mask:0xf bank_mask:0xf
	v_mul_f32_dpp v46, v46, v46 row_shr:1 row_mask:0xf bank_mask:0xf
	v_mul_f32_dpp v47, v47, v47 row_shr:1 row_mask:0xf bank_mask:0xf
	v_fmac_f32_dpp v48, v48, v44 row_shr:2 row_mask:0xf bank_mask:0xf
	v_fmac_f32_dpp v49, v49, v45 row_shr:2 row_mask:0xf bank_mask:0xf
	v_fmac_f32_dpp v50, v50, v46 row_shr:2 row_mask:0xf bank_mask:0xf
	v_fmac_f32_dpp v51, v51, v47 row_shr:2 row_mask:0xf bank_mask:0xf
	v_mul_f32_dpp v44, v44, v44 row_shr:2 row_mask:0xf bank_mask:0xf
	v_mul_f32_dpp v45, v45, v45 row_shr:2 row_mask:0xf bank_mask:0xf
	v_mul_f32_dpp v46, v46, v46 row_shr:2 row_mask:0xf bank_mask:0xf
	v_mul_f32_dpp v47, v47, v47 row_shr:2 row_mask:0xf bank_mask:0xf
	v_fmac_f32_dpp v48, v48, v44 row_shr:4 row_mask:0xf bank_mask:0xf
	v_fmac_f32_dpp v49, v49, v45 row_shr:4 row_mask:0xf bank_mask:0xf
	v_fmac_f32_dpp v50, v50, v46 row_shr:4 row_mask:0xf bank_mask:0xf
	v_fmac_f32_dpp v51, v51, v47 row_shr:4 row_mask:0xf bank_mask:0xf
	v_mul_f32_dpp v44, v44, v44 row_shr:4 row_mask:0xf bank_mask:0xf
	v_mul_f32_dpp v45, v45, v45 row_shr:4 row_mask:0xf bank_mask:0xf
	v_mul_f32_dpp v46, v46, v46 row_shr:4 row_mask:0xf bank_mask:0xf
	v_mul_f32_dpp v47, v47, v47 row_shr:4 row_mask:0xf bank_mask:0xf
	v_fmac_f32_dpp v48, v48, v44 row_shr:8 row_mask:0xf bank_mask:0xf
	v_fmac_f32_dpp v49, v49, v45 row_shr:8 row_mask:0xf bank_mask:0xf
	v_fmac_f32_dpp v50, v50, v46 row_shr:8 row_mask:0xf bank_mask:0xf
	v_fmac_f32_dpp v51, v51, v47 row_shr:8 row_mask:0xf bank_mask:0xf
	v_mul_f32_dpp v44, v44, v44 row_shr:8 row_mask:0xf bank_mask:0xf
	v_mul_f32_dpp v45, v45, v45 row_shr:8 row_mask:0xf bank_mask:0xf
	v_mul_f32_dpp v46, v46, v46 row_shr:8 row_mask:0xf bank_mask:0xf
	v_mul_f32_dpp v47, v47, v47 row_shr:8 row_mask:0xf bank_mask:0xf
	v_fmac_f32_dpp v48, v48, v44 row_bcast:15 row_mask:0xa bank_mask:0xf
	v_fmac_f32_dpp v49, v49, v45 row_bcast:15 row_mask:0xa bank_mask:0xf
	v_fmac_f32_dpp v50, v50, v46 row_bcast:15 row_mask:0xa bank_mask:0xf
	v_fmac_f32_dpp v51, v51, v47 row_bcast:15 row_mask:0xa bank_mask:0xf
	v_mul_f32_dpp v44, v44, v44 row_bcast:15 row_mask:0xa bank_mask:0xf
	v_mul_f32_dpp v45, v45, v45 row_bcast:15 row_mask:0xa bank_mask:0xf
	v_mul_f32_dpp v46, v46, v46 row_bcast:15 row_mask:0xa bank_mask:0xf
	v_mul_f32_dpp v47, v47, v47 row_bcast:15 row_mask:0xa bank_mask:0xf
	ds_read_b128 v[0:3], v234 offset:39136
	v_exp_f32_e32 v4, v4
	v_exp_f32_e32 v5, v5
	v_exp_f32_e32 v6, v6
	v_exp_f32_e32 v7, v7
	v_exp_f32_e32 v20, v20
	v_exp_f32_e32 v21, v21
	v_exp_f32_e32 v22, v22
	v_exp_f32_e32 v23, v23
	v_pk_add_f32 v[4:5], v[4:5], v[240:241] op_sel_hi:[1,0]
	v_pk_add_f32 v[6:7], v[6:7], v[240:241] op_sel_hi:[1,0]
	v_pk_add_f32 v[20:21], v[20:21], v[240:241] op_sel_hi:[1,0]
	v_pk_add_f32 v[22:23], v[22:23], v[240:241] op_sel_hi:[1,0]
	v_rcp_f32_e32 v4, v4
	v_rcp_f32_e32 v5, v5
	v_rcp_f32_e32 v6, v6
	v_rcp_f32_e32 v7, v7
	v_rcp_f32_e32 v20, v20
	v_rcp_f32_e32 v21, v21
	v_rcp_f32_e32 v22, v22
	v_rcp_f32_e32 v23, v23
	v_mul_f32_e32 v200, v53, v20
	v_mul_f32_e32 v201, v54, v21
	v_mul_f32_e32 v202, v58, v22
	v_mul_f32_e32 v203, v59, v23
	s_waitcnt lgkmcnt(0)
; #define LAS __attribute__((address_space(3)))
; __device__ __forceinline__ float ex2(float x) { return __builtin_amdgcn_exp2f(x); }
; __device__ __forceinline__ float rcpf_(float x) { return __builtin_amdgcn_rcpf(x); }
; __device__ __forceinline__ void lru_phase(const Ptrs& P, LAS unsigned char* lds, int G, int wave, int lane, int tid) {
;     ...
; #pragma unroll
;             for (int i4 = 0; i4 < 4; ++i4) { if (mt == 2 && i4 >= 2) continue;
;                 const int s = 2 * mt + (i4 >> 1), half = i4 & 1, ch0 = 16 * s + 8 * half + 4 * hh;
;                 const f32x4 ls2 = *(const LAS f32x4*)(par + 7 * LB + ch0);
;                 float A4[4], B4[4];
; #pragma unroll
;                 for (int q = 0; q < 4; ++q) { const int i = 4 * i4 + q;
;                     const float rg = rcpf_(1.0f + ex2(gr[i])), ig = rcpf_(1.0f + ex2(gi[i]));
;                     const float la2 = ls2[q] * rg, a = ex2(la2), xx = (2.0f * LN2) * la2;
;                     const float poly = -xx * (1.0f + xx * (0.5f + xx * ((1.0f / 6.0f) + xx * ((1.0f / 24.0f) + xx * (1.0f / 120.0f)))));
;                     const float om = (xx > -0.25f) ? poly : (1.0f - a * a);
;                     A4[q] = a; B4[q] = __builtin_amdgcn_sqrtf(om) * (ig * xc[s][half][q]); }
;                 asm volatile("s_nop 1\n\t"
;                     LRU_DPP4("row_shr:1 row_mask:0xf bank_mask:0xf") LRU_DPP4("row_shr:2 row_mask:0xf bank_mask:0xf") LRU_DPP4("row_shr:4 row_mask:0xf bank_mask:0xf")
;                     LRU_DPP4("row_shr:8 row_mask:0xf bank_mask:0xf") LRU_DPP4("row_bcast:15 row_mask:0xa bank_mask:0xf")
;                     : "+v"(A4[0]), "+v"(A4[1]), "+v"(A4[2]), "+v"(A4[3]), "+v"(B4[0]), "+v"(B4[1]), "+v"(B4[2]), "+v"(B4[3]));
; #pragma unroll
;                 for (int q = 0; q < 4; ++q) { Av[s][half][q] = A4[q]; xc[s][half][q] = B4[q]; }
;                 __builtin_amdgcn_sched_barrier(0); }
	v_pk_mul_f32 v[4:5], v[4:5], v[0:1]
	v_pk_mul_f32 v[6:7], v[6:7], v[2:3]
	v_pk_mul_f32 v[204:205], v[4:5], v[242:243] op_sel_hi:[1,0]
	v_pk_mul_f32 v[206:207], v[6:7], v[242:243] op_sel_hi:[1,0]
	v_exp_f32_e32 v52, v4
	v_exp_f32_e32 v53, v5
	v_exp_f32_e32 v54, v6
	v_exp_f32_e32 v55, v7
	v_pk_fma_f32 v[208:209], v[204:205], v[244:245], v[238:239] op_sel_hi:[1,0,0]
	v_pk_fma_f32 v[210:211], v[206:207], v[244:245], v[238:239] op_sel_hi:[1,0,0]
	v_pk_fma_f32 v[208:209], v[204:205], v[208:209], v[246:247] op_sel_hi:[1,1,0]
	v_pk_fma_f32 v[210:211], v[206:207], v[210:211], v[246:247] op_sel_hi:[1,1,0]
	v_pk_fma_f32 v[208:209], v[204:205], v[208:209], v[248:249] op_sel_hi:[1,1,0]
	v_pk_fma_f32 v[210:211], v[206:207], v[210:211], v[248:249] op_sel_hi:[1,1,0]
	v_pk_fma_f32 v[208:209], v[204:205], v[208:209], v[240:241] op_sel_hi:[1,1,0]
	v_pk_fma_f32 v[210:211], v[206:207], v[210:211], v[240:241] op_sel_hi:[1,1,0]
	v_pk_mul_f32 v[208:209], v[208:209], v[204:205] neg_lo:[0,1] neg_hi:[0,1]
	v_pk_mul_f32 v[210:211], v[210:211], v[206:207] neg_lo:[0,1] neg_hi:[0,1]
	v_pk_fma_f32 v[212:213], v[52:53], v[52:53], v[240:241] op_sel_hi:[1,1,0] neg_lo:[1,0,0] neg_hi:[1,0,0]
	v_pk_fma_f32 v[214:215], v[54:55], v[54:55], v[240:241] op_sel_hi:[1,1,0] neg_lo:[1,0,0] neg_hi:[1,0,0]
	v_cmp_lt_f32_e64 s[70:71], s29, v204
	v_cmp_lt_f32_e64 s[72:73], s29, v205
	v_cmp_lt_f32_e64 s[74:75], s29, v206
	v_cmp_lt_f32_e64 s[76:77], s29, v207
	v_cndmask_b32_e64 v212, v212, v208, s[70:71]
	v_cndmask_b32_e64 v213, v213, v209, s[72:73]
	v_cndmask_b32_e64 v214, v214, v210, s[74:75]
	v_cndmask_b32_e64 v215, v215, v211, s[76:77]
	v_sqrt_f32_e32 v212, v212
	v_sqrt_f32_e32 v213, v213
	v_sqrt_f32_e32 v214, v214
	v_sqrt_f32_e32 v215, v215
	v_pk_mul_f32 v[56:57], v[200:201], v[212:213]
	v_pk_mul_f32 v[58:59], v[202:203], v[214:215]
	s_nop 1
	v_fmac_f32_dpp v56, v56, v52 row_shr:1 row_mask:0xf bank_mask:0xf
	v_fmac_f32_dpp v57, v57, v53 row_shr:1 row_mask:0xf bank_mask:0xf
	v_fmac_f32_dpp v58, v58, v54 row_shr:1 row_mask:0xf bank_mask:0xf
	v_fmac_f32_dpp v59, v59, v55 row_shr:1 row_mask:0xf bank_mask:0xf
	v_mul_f32_dpp v52, v52, v52 row_shr:1 row_mask:0xf bank_mask:0xf
	v_mul_f32_dpp v53, v53, v53 row_shr:1 row_mask:0xf bank_mask:0xf
	v_mul_f32_dpp v54, v54, v54 row_shr:1 row_mask:0xf bank_mask:0xf
	v_mul_f32_dpp v55, v55, v55 row_shr:1 row_mask:0xf bank_mask:0xf
	v_fmac_f32_dpp v56, v56, v52 row_shr:2 row_mask:0xf bank_mask:0xf
	v_fmac_f32_dpp v57, v57, v53 row_shr:2 row_mask:0xf bank_mask:0xf
	v_fmac_f32_dpp v58, v58, v54 row_shr:2 row_mask:0xf bank_mask:0xf
	v_fmac_f32_dpp v59, v59, v55 row_shr:2 row_mask:0xf bank_mask:0xf
	v_mul_f32_dpp v52, v52, v52 row_shr:2 row_mask:0xf bank_mask:0xf
	v_mul_f32_dpp v53, v53, v53 row_shr:2 row_mask:0xf bank_mask:0xf
	v_mul_f32_dpp v54, v54, v54 row_shr:2 row_mask:0xf bank_mask:0xf
	v_mul_f32_dpp v55, v55, v55 row_shr:2 row_mask:0xf bank_mask:0xf
	v_fmac_f32_dpp v56, v56, v52 row_shr:4 row_mask:0xf bank_mask:0xf
	v_fmac_f32_dpp v57, v57, v53 row_shr:4 row_mask:0xf bank_mask:0xf
	v_fmac_f32_dpp v58, v58, v54 row_shr:4 row_mask:0xf bank_mask:0xf
	v_fmac_f32_dpp v59, v59, v55 row_shr:4 row_mask:0xf bank_mask:0xf
	v_mul_f32_dpp v52, v52, v52 row_shr:4 row_mask:0xf bank_mask:0xf
	v_mul_f32_dpp v53, v53, v53 row_shr:4 row_mask:0xf bank_mask:0xf
	v_mul_f32_dpp v54, v54, v54 row_shr:4 row_mask:0xf bank_mask:0xf
	v_mul_f32_dpp v55, v55, v55 row_shr:4 row_mask:0xf bank_mask:0xf
	v_fmac_f32_dpp v56, v56, v52 row_shr:8 row_mask:0xf bank_mask:0xf
	v_fmac_f32_dpp v57, v57, v53 row_shr:8 row_mask:0xf bank_mask:0xf
	v_fmac_f32_dpp v58, v58, v54 row_shr:8 row_mask:0xf bank_mask:0xf
	v_fmac_f32_dpp v59, v59, v55 row_shr:8 row_mask:0xf bank_mask:0xf
	v_mul_f32_dpp v52, v52, v52 row_shr:8 row_mask:0xf bank_mask:0xf
	v_mul_f32_dpp v53, v53, v53 row_shr:8 row_mask:0xf bank_mask:0xf
	v_mul_f32_dpp v54, v54, v54 row_shr:8 row_mask:0xf bank_mask:0xf
	v_mul_f32_dpp v55, v55, v55 row_shr:8 row_mask:0xf bank_mask:0xf
	v_fmac_f32_dpp v56, v56, v52 row_bcast:15 row_mask:0xa bank_mask:0xf
	v_fmac_f32_dpp v57, v57, v53 row_bcast:15 row_mask:0xa bank_mask:0xf
	v_fmac_f32_dpp v58, v58, v54 row_bcast:15 row_mask:0xa bank_mask:0xf
	v_fmac_f32_dpp v59, v59, v55 row_bcast:15 row_mask:0xa bank_mask:0xf
	v_mul_f32_dpp v52, v52, v52 row_bcast:15 row_mask:0xa bank_mask:0xf
	v_mul_f32_dpp v53, v53, v53 row_bcast:15 row_mask:0xa bank_mask:0xf
	v_mul_f32_dpp v54, v54, v54 row_bcast:15 row_mask:0xa bank_mask:0xf
	v_mul_f32_dpp v55, v55, v55 row_bcast:15 row_mask:0xa bank_mask:0xf
	ds_read_b128 v[0:3], v234 offset:39168
	v_exp_f32_e32 v8, v8
	v_exp_f32_e32 v9, v9
	v_exp_f32_e32 v10, v10
	v_exp_f32_e32 v11, v11
	v_exp_f32_e32 v24, v24
	v_exp_f32_e32 v25, v25
	v_exp_f32_e32 v26, v26
	v_exp_f32_e32 v27, v27
	v_pk_add_f32 v[8:9], v[8:9], v[240:241] op_sel_hi:[1,0]
	v_pk_add_f32 v[10:11], v[10:11], v[240:241] op_sel_hi:[1,0]
	v_pk_add_f32 v[24:25], v[24:25], v[240:241] op_sel_hi:[1,0]
	v_pk_add_f32 v[26:27], v[26:27], v[240:241] op_sel_hi:[1,0]
	v_rcp_f32_e32 v8, v8
	v_rcp_f32_e32 v9, v9
	v_rcp_f32_e32 v10, v10
	v_rcp_f32_e32 v11, v11
	v_rcp_f32_e32 v24, v24
	v_rcp_f32_e32 v25, v25
	v_rcp_f32_e32 v26, v26
	v_rcp_f32_e32 v27, v27
	v_mul_f32_e32 v200, v61, v24
	v_mul_f32_e32 v201, v62, v25
	v_mul_f32_e32 v202, v66, v26
	v_mul_f32_e32 v203, v67, v27
	s_waitcnt lgkmcnt(0)
; #define LAS __attribute__((address_space(3)))
; __device__ __forceinline__ float ex2(float x) { return __builtin_amdgcn_exp2f(x); }
; __device__ __forceinline__ float rcpf_(float x) { return __builtin_amdgcn_rcpf(x); }
; __device__ __forceinline__ void lru_phase(const Ptrs& P, LAS unsigned char* lds, int G, int wave, int lane, int tid) {
;     ...
; #pragma unroll
;             for (int i4 = 0; i4 < 4; ++i4) { if (mt == 2 && i4 >= 2) continue;
;                 const int s = 2 * mt + (i4 >> 1), half = i4 & 1, ch0 = 16 * s + 8 * half + 4 * hh;
;                 const f32x4 ls2 = *(const LAS f32x4*)(par + 7 * LB + ch0);
;                 float A4[4], B4[4];
; #pragma unroll
;                 for (int q = 0; q < 4; ++q) { const int i = 4 * i4 + q;
;                     const float rg = rcpf_(1.0f + ex2(gr[i])), ig = rcpf_(1.0f + ex2(gi[i]));
;                     const float la2 = ls2[q] * rg, a = ex2(la2), xx = (2.0f * LN2) * la2;
;                     const float poly = -xx * (1.0f + xx * (0.5f + xx * ((1.0f / 6.0f) + xx * ((1.0f / 24.0f) + xx * (1.0f / 120.0f)))));
;                     const float om = (xx > -0.25f) ? poly : (1.0f - a * a);
;                     A4[q] = a; B4[q] = __builtin_amdgcn_sqrtf(om) * (ig * xc[s][half][q]); }
;                 asm volatile("s_nop 1\n\t"
;                     LRU_DPP4("row_shr:1 row_mask:0xf bank_mask:0xf") LRU_DPP4("row_shr:2 row_mask:0xf bank_mask:0xf") LRU_DPP4("row_shr:4 row_mask:0xf bank_mask:0xf")
;                     LRU_DPP4("row_shr:8 row_mask:0xf bank_mask:0xf") LRU_DPP4("row_bcast:15 row_mask:0xa bank_mask:0xf")
;                     : "+v"(A4[0]), "+v"(A4[1]), "+v"(A4[2]), "+v"(A4[3]), "+v"(B4[0]), "+v"(B4[1]), "+v"(B4[2]), "+v"(B4[3]));
; #pragma unroll
;                 for (int q = 0; q < 4; ++q) { Av[s][half][q] = A4[q]; xc[s][half][q] = B4[q]; }
;                 __builtin_amdgcn_sched_barrier(0); }
	v_pk_mul_f32 v[8:9], v[8:9], v[0:1]
	v_pk_mul_f32 v[10:11], v[10:11], v[2:3]
	v_pk_mul_f32 v[204:205], v[8:9], v[242:243] op_sel_hi:[1,0]
	v_pk_mul_f32 v[206:207], v[10:11], v[242:243] op_sel_hi:[1,0]
	v_exp_f32_e32 v60, v8
	v_exp_f32_e32 v61, v9
	v_exp_f32_e32 v62, v10
	v_exp_f32_e32 v63, v11
	v_pk_fma_f32 v[208:209], v[204:205], v[244:245], v[238:239] op_sel_hi:[1,0,0]
	v_pk_fma_f32 v[210:211], v[206:207], v[244:245], v[238:239] op_sel_hi:[1,0,0]
	v_pk_fma_f32 v[208:209], v[204:205], v[208:209], v[246:247] op_sel_hi:[1,1,0]
	v_pk_fma_f32 v[210:211], v[206:207], v[210:211], v[246:247] op_sel_hi:[1,1,0]
	v_pk_fma_f32 v[208:209], v[204:205], v[208:209], v[248:249] op_sel_hi:[1,1,0]
	v_pk_fma_f32 v[210:211], v[206:207], v[210:211], v[248:249] op_sel_hi:[1,1,0]
	v_pk_fma_f32 v[208:209], v[204:205], v[208:209], v[240:241] op_sel_hi:[1,1,0]
	v_pk_fma_f32 v[210:211], v[206:207], v[210:211], v[240:241] op_sel_hi:[1,1,0]
	v_pk_mul_f32 v[208:209], v[208:209], v[204:205] neg_lo:[0,1] neg_hi:[0,1]
	v_pk_mul_f32 v[210:211], v[210:211], v[206:207] neg_lo:[0,1] neg_hi:[0,1]
	v_pk_fma_f32 v[212:213], v[60:61], v[60:61], v[240:241] op_sel_hi:[1,1,0] neg_lo:[1,0,0] neg_hi:[1,0,0]
	v_pk_fma_f32 v[214:215], v[62:63], v[62:63], v[240:241] op_sel_hi:[1,1,0] neg_lo:[1,0,0] neg_hi:[1,0,0]
	v_cmp_lt_f32_e64 s[70:71], s29, v204
	v_cmp_lt_f32_e64 s[72:73], s29, v205
	v_cmp_lt_f32_e64 s[74:75], s29, v206
	v_cmp_lt_f32_e64 s[76:77], s29, v207
	v_cndmask_b32_e64 v212, v212, v208, s[70:71]
	v_cndmask_b32_e64 v213, v213, v209, s[72:73]
	v_cndmask_b32_e64 v214, v214, v210, s[74:75]
	v_cndmask_b32_e64 v215, v215, v211, s[76:77]
	v_sqrt_f32_e32 v212, v212
	v_sqrt_f32_e32 v213, v213
	v_sqrt_f32_e32 v214, v214
	v_sqrt_f32_e32 v215, v215
	v_pk_mul_f32 v[64:65], v[200:201], v[212:213]
	v_pk_mul_f32 v[66:67], v[202:203], v[214:215]
	s_nop 1
	v_fmac_f32_dpp v64, v64, v60 row_shr:1 row_mask:0xf bank_mask:0xf
	v_fmac_f32_dpp v65, v65, v61 row_shr:1 row_mask:0xf bank_mask:0xf
	v_fmac_f32_dpp v66, v66, v62 row_shr:1 row_mask:0xf bank_mask:0xf
	v_fmac_f32_dpp v67, v67, v63 row_shr:1 row_mask:0xf bank_mask:0xf
	v_mul_f32_dpp v60, v60, v60 row_shr:1 row_mask:0xf bank_mask:0xf
	v_mul_f32_dpp v61, v61, v61 row_shr:1 row_mask:0xf bank_mask:0xf
	v_mul_f32_dpp v62, v62, v62 row_shr:1 row_mask:0xf bank_mask:0xf
	v_mul_f32_dpp v63, v63, v63 row_shr:1 row_mask:0xf bank_mask:0xf
	v_fmac_f32_dpp v64, v64, v60 row_shr:2 row_mask:0xf bank_mask:0xf
	v_fmac_f32_dpp v65, v65, v61 row_shr:2 row_mask:0xf bank_mask:0xf
	v_fmac_f32_dpp v66, v66, v62 row_shr:2 row_mask:0xf bank_mask:0xf
	v_fmac_f32_dpp v67, v67, v63 row_shr:2 row_mask:0xf bank_mask:0xf
	v_mul_f32_dpp v60, v60, v60 row_shr:2 row_mask:0xf bank_mask:0xf
	v_mul_f32_dpp v61, v61, v61 row_shr:2 row_mask:0xf bank_mask:0xf
	v_mul_f32_dpp v62, v62, v62 row_shr:2 row_mask:0xf bank_mask:0xf
	v_mul_f32_dpp v63, v63, v63 row_shr:2 row_mask:0xf bank_mask:0xf
	v_fmac_f32_dpp v64, v64, v60 row_shr:4 row_mask:0xf bank_mask:0xf
	v_fmac_f32_dpp v65, v65, v61 row_shr:4 row_mask:0xf bank_mask:0xf
	v_fmac_f32_dpp v66, v66, v62 row_shr:4 row_mask:0xf bank_mask:0xf
	v_fmac_f32_dpp v67, v67, v63 row_shr:4 row_mask:0xf bank_mask:0xf
	v_mul_f32_dpp v60, v60, v60 row_shr:4 row_mask:0xf bank_mask:0xf
	v_mul_f32_dpp v61, v61, v61 row_shr:4 row_mask:0xf bank_mask:0xf
	v_mul_f32_dpp v62, v62, v62 row_shr:4 row_mask:0xf bank_mask:0xf
	v_mul_f32_dpp v63, v63, v63 row_shr:4 row_mask:0xf bank_mask:0xf
	v_fmac_f32_dpp v64, v64, v60 row_shr:8 row_mask:0xf bank_mask:0xf
	v_fmac_f32_dpp v65, v65, v61 row_shr:8 row_mask:0xf bank_mask:0xf
	v_fmac_f32_dpp v66, v66, v62 row_shr:8 row_mask:0xf bank_mask:0xf
	v_fmac_f32_dpp v67, v67, v63 row_shr:8 row_mask:0xf bank_mask:0xf
	v_mul_f32_dpp v60, v60, v60 row_shr:8 row_mask:0xf bank_mask:0xf
	v_mul_f32_dpp v61, v61, v61 row_shr:8 row_mask:0xf bank_mask:0xf
	v_mul_f32_dpp v62, v62, v62 row_shr:8 row_mask:0xf bank_mask:0xf
	v_mul_f32_dpp v63, v63, v63 row_shr:8 row_mask:0xf bank_mask:0xf
	v_fmac_f32_dpp v64, v64, v60 row_bcast:15 row_mask:0xa bank_mask:0xf
	v_fmac_f32_dpp v65, v65, v61 row_bcast:15 row_mask:0xa bank_mask:0xf
	v_fmac_f32_dpp v66, v66, v62 row_bcast:15 row_mask:0xa bank_mask:0xf
	v_fmac_f32_dpp v67, v67, v63 row_bcast:15 row_mask:0xa bank_mask:0xf
	v_mul_f32_dpp v60, v60, v60 row_bcast:15 row_mask:0xa bank_mask:0xf
	v_mul_f32_dpp v61, v61, v61 row_bcast:15 row_mask:0xa bank_mask:0xf
	v_mul_f32_dpp v62, v62, v62 row_bcast:15 row_mask:0xa bank_mask:0xf
	v_mul_f32_dpp v63, v63, v63 row_bcast:15 row_mask:0xa bank_mask:0xf
	ds_read_b128 v[0:3], v234 offset:39200
	v_exp_f32_e32 v12, v12
	v_exp_f32_e32 v13, v13
	v_exp_f32_e32 v14, v14
	v_exp_f32_e32 v15, v15
	v_exp_f32_e32 v28, v28
	v_exp_f32_e32 v29, v29
	v_exp_f32_e32 v30, v30
	v_exp_f32_e32 v31, v31
	v_pk_add_f32 v[12:13], v[12:13], v[240:241] op_sel_hi:[1,0]
	v_pk_add_f32 v[14:15], v[14:15], v[240:241] op_sel_hi:[1,0]
	v_pk_add_f32 v[28:29], v[28:29], v[240:241] op_sel_hi:[1,0]
	v_pk_add_f32 v[30:31], v[30:31], v[240:241] op_sel_hi:[1,0]
	v_rcp_f32_e32 v12, v12
	v_rcp_f32_e32 v13, v13
	v_rcp_f32_e32 v14, v14
	v_rcp_f32_e32 v15, v15
	v_rcp_f32_e32 v28, v28
	v_rcp_f32_e32 v29, v29
	v_rcp_f32_e32 v30, v30
	v_rcp_f32_e32 v31, v31
	v_mul_f32_e32 v200, v69, v28
	v_mul_f32_e32 v201, v70, v29
	v_mul_f32_e32 v202, v74, v30
	v_mul_f32_e32 v203, v75, v31
	s_waitcnt lgkmcnt(0)
; #define LAS __attribute__((address_space(3)))
; __device__ __forceinline__ float ex2(float x) { return __builtin_amdgcn_exp2f(x); }
; __device__ __forceinline__ float rcpf_(float x) { return __builtin_amdgcn_rcpf(x); }
; __device__ __forceinline__ void lru_phase(const Ptrs& P, LAS unsigned char* lds, int G, int wave, int lane, int tid) {
;     ...
; #pragma unroll
;             for (int i4 = 0; i4 < 4; ++i4) { if (mt == 2 && i4 >= 2) continue;
;                 const int s = 2 * mt + (i4 >> 1), half = i4 & 1, ch0 = 16 * s + 8 * half + 4 * hh;
;                 const f32x4 ls2 = *(const LAS f32x4*)(par + 7 * LB + ch0);
;                 float A4[4], B4[4];
; #pragma unroll
;                 for (int q = 0; q < 4; ++q) { const int i = 4 * i4 + q;
;                     const float rg = rcpf_(1.0f + ex2(gr[i])), ig = rcpf_(1.0f + ex2(gi[i]));
;                     const float la2 = ls2[q] * rg, a = ex2(la2), xx = (2.0f * LN2) * la2;
;                     const float poly = -xx * (1.0f + xx * (0.5f + xx * ((1.0f / 6.0f) + xx * ((1.0f / 24.0f) + xx * (1.0f / 120.0f)))));
;                     const float om = (xx > -0.25f) ? poly : (1.0f - a * a);
;                     A4[q] = a; B4[q] = __builtin_amdgcn_sqrtf(om) * (ig * xc[s][half][q]); }
;                 asm volatile("s_nop 1\n\t"
;                     LRU_DPP4("row_shr:1 row_mask:0xf bank_mask:0xf") LRU_DPP4("row_shr:2 row_mask:0xf bank_mask:0xf") LRU_DPP4("row_shr:4 row_mask:0xf bank_mask:0xf")
;                     LRU_DPP4("row_shr:8 row_mask:0xf bank_mask:0xf") LRU_DPP4("row_bcast:15 row_mask:0xa bank_mask:0xf")
;                     : "+v"(A4[0]), "+v"(A4[1]), "+v"(A4[2]), "+v"(A4[3]), "+v"(B4[0]), "+v"(B4[1]), "+v"(B4[2]), "+v"(B4[3]));
; #pragma unroll
;                 for (int q = 0; q < 4; ++q) { Av[s][half][q] = A4[q]; xc[s][half][q] = B4[q]; }
;                 __builtin_amdgcn_sched_barrier(0); }
	v_pk_mul_f32 v[12:13], v[12:13], v[0:1]
	v_pk_mul_f32 v[14:15], v[14:15], v[2:3]
	v_pk_mul_f32 v[204:205], v[12:13], v[242:243] op_sel_hi:[1,0]
	v_pk_mul_f32 v[206:207], v[14:15], v[242:243] op_sel_hi:[1,0]
	v_exp_f32_e32 v68, v12
	v_exp_f32_e32 v69, v13
	v_exp_f32_e32 v70, v14
	v_exp_f32_e32 v71, v15
	v_pk_fma_f32 v[208:209], v[204:205], v[244:245], v[238:239] op_sel_hi:[1,0,0]
	v_pk_fma_f32 v[210:211], v[206:207], v[244:245], v[238:239] op_sel_hi:[1,0,0]
	v_pk_fma_f32 v[208:209], v[204:205], v[208:209], v[246:247] op_sel_hi:[1,1,0]
	v_pk_fma_f32 v[210:211], v[206:207], v[210:211], v[246:247] op_sel_hi:[1,1,0]
	v_pk_fma_f32 v[208:209], v[204:205], v[208:209], v[248:249] op_sel_hi:[1,1,0]
	v_pk_fma_f32 v[210:211], v[206:207], v[210:211], v[248:249] op_sel_hi:[1,1,0]
	v_pk_fma_f32 v[208:209], v[204:205], v[208:209], v[240:241] op_sel_hi:[1,1,0]
	v_pk_fma_f32 v[210:211], v[206:207], v[210:211], v[240:241] op_sel_hi:[1,1,0]
	v_pk_mul_f32 v[208:209], v[208:209], v[204:205] neg_lo:[0,1] neg_hi:[0,1]
	v_pk_mul_f32 v[210:211], v[210:211], v[206:207] neg_lo:[0,1] neg_hi:[0,1]
	v_pk_fma_f32 v[212:213], v[68:69], v[68:69], v[240:241] op_sel_hi:[1,1,0] neg_lo:[1,0,0] neg_hi:[1,0,0]
	v_pk_fma_f32 v[214:215], v[70:71], v[70:71], v[240:241] op_sel_hi:[1,1,0] neg_lo:[1,0,0] neg_hi:[1,0,0]
	v_cmp_lt_f32_e64 s[70:71], s29, v204
	v_cmp_lt_f32_e64 s[72:73], s29, v205
	v_cmp_lt_f32_e64 s[74:75], s29, v206
	v_cmp_lt_f32_e64 s[76:77], s29, v207
	v_cndmask_b32_e64 v212, v212, v208, s[70:71]
	v_cndmask_b32_e64 v213, v213, v209, s[72:73]
	v_cndmask_b32_e64 v214, v214, v210, s[74:75]
	v_cndmask_b32_e64 v215, v215, v211, s[76:77]
	v_sqrt_f32_e32 v212, v212
	v_sqrt_f32_e32 v213, v213
	v_sqrt_f32_e32 v214, v214
	v_sqrt_f32_e32 v215, v215
	v_pk_mul_f32 v[72:73], v[200:201], v[212:213]
	v_pk_mul_f32 v[74:75], v[202:203], v[214:215]
	s_nop 1
	v_fmac_f32_dpp v72, v72, v68 row_shr:1 row_mask:0xf bank_mask:0xf
	v_fmac_f32_dpp v73, v73, v69 row_shr:1 row_mask:0xf bank_mask:0xf
	v_fmac_f32_dpp v74, v74, v70 row_shr:1 row_mask:0xf bank_mask:0xf
	v_fmac_f32_dpp v75, v75, v71 row_shr:1 row_mask:0xf bank_mask:0xf
	v_mul_f32_dpp v68, v68, v68 row_shr:1 row_mask:0xf bank_mask:0xf
	v_mul_f32_dpp v69, v69, v69 row_shr:1 row_mask:0xf bank_mask:0xf
	v_mul_f32_dpp v70, v70, v70 row_shr:1 row_mask:0xf bank_mask:0xf
	v_mul_f32_dpp v71, v71, v71 row_shr:1 row_mask:0xf bank_mask:0xf
	v_fmac_f32_dpp v72, v72, v68 row_shr:2 row_mask:0xf bank_mask:0xf
	v_fmac_f32_dpp v73, v73, v69 row_shr:2 row_mask:0xf bank_mask:0xf
	v_fmac_f32_dpp v74, v74, v70 row_shr:2 row_mask:0xf bank_mask:0xf
	v_fmac_f32_dpp v75, v75, v71 row_shr:2 row_mask:0xf bank_mask:0xf
	v_mul_f32_dpp v68, v68, v68 row_shr:2 row_mask:0xf bank_mask:0xf
	v_mul_f32_dpp v69, v69, v69 row_shr:2 row_mask:0xf bank_mask:0xf
	v_mul_f32_dpp v70, v70, v70 row_shr:2 row_mask:0xf bank_mask:0xf
	v_mul_f32_dpp v71, v71, v71 row_shr:2 row_mask:0xf bank_mask:0xf
	v_fmac_f32_dpp v72, v72, v68 row_shr:4 row_mask:0xf bank_mask:0xf
	v_fmac_f32_dpp v73, v73, v69 row_shr:4 row_mask:0xf bank_mask:0xf
	v_fmac_f32_dpp v74, v74, v70 row_shr:4 row_mask:0xf bank_mask:0xf
	v_fmac_f32_dpp v75, v75, v71 row_shr:4 row_mask:0xf bank_mask:0xf
	v_mul_f32_dpp v68, v68, v68 row_shr:4 row_mask:0xf bank_mask:0xf
	v_mul_f32_dpp v69, v69, v69 row_shr:4 row_mask:0xf bank_mask:0xf
	v_mul_f32_dpp v70, v70, v70 row_shr:4 row_mask:0xf bank_mask:0xf
	v_mul_f32_dpp v71, v71, v71 row_shr:4 row_mask:0xf bank_mask:0xf
	v_fmac_f32_dpp v72, v72, v68 row_shr:8 row_mask:0xf bank_mask:0xf
	v_fmac_f32_dpp v73, v73, v69 row_shr:8 row_mask:0xf bank_mask:0xf
	v_fmac_f32_dpp v74, v74, v70 row_shr:8 row_mask:0xf bank_mask:0xf
	v_fmac_f32_dpp v75, v75, v71 row_shr:8 row_mask:0xf bank_mask:0xf
	v_mul_f32_dpp v68, v68, v68 row_shr:8 row_mask:0xf bank_mask:0xf
	v_mul_f32_dpp v69, v69, v69 row_shr:8 row_mask:0xf bank_mask:0xf
	v_mul_f32_dpp v70, v70, v70 row_shr:8 row_mask:0xf bank_mask:0xf
	v_mul_f32_dpp v71, v71, v71 row_shr:8 row_mask:0xf bank_mask:0xf
	v_fmac_f32_dpp v72, v72, v68 row_bcast:15 row_mask:0xa bank_mask:0xf
	v_fmac_f32_dpp v73, v73, v69 row_bcast:15 row_mask:0xa bank_mask:0xf
	v_fmac_f32_dpp v74, v74, v70 row_bcast:15 row_mask:0xa bank_mask:0xf
	v_fmac_f32_dpp v75, v75, v71 row_bcast:15 row_mask:0xa bank_mask:0xf
	v_mul_f32_dpp v68, v68, v68 row_bcast:15 row_mask:0xa bank_mask:0xf
	v_mul_f32_dpp v69, v69, v69 row_bcast:15 row_mask:0xa bank_mask:0xf
	v_mul_f32_dpp v70, v70, v70 row_bcast:15 row_mask:0xa bank_mask:0xf
	v_mul_f32_dpp v71, v71, v71 row_bcast:15 row_mask:0xa bank_mask:0xf

; #define LAS __attribute__((address_space(3)))
; __device__ __forceinline__ void lru_phase(const Ptrs& P, LAS unsigned char* lds, int G, int wave, int lane, int tid) {
;     ...
;         for (int mt = 0; mt < 3; ++mt) {
;             f32x16 gr, gi;
; #pragma unroll
;             for (int i = 0; i < 16; ++i) { gr[i] = 0.f; gi[i] = 0.f; }
;             const LAS bf16x8* wa = (const LAS bf16x8*)(lds + L_WGF) + (size_t)(mt * 6) * 64 + lane;
;             const LAS bf16x8* wb = (const LAS bf16x8*)(lds + L_WGF) + (size_t)((3 + mt) * 6) * 64 + lane;
; #pragma unroll
;             for (int s = 0; s < 5; ++s) { gr = MFMA32(wa[s * 64], xf[s], gr); gi = MFMA32(wb[s * 64], xf[s], gi); }
;             gr = MFMA32(wa[5 * 64], xone, gr); gi = MFMA32(wb[5 * 64], xone, gi);
;             __builtin_amdgcn_sched_barrier(0);
; #pragma unroll
;             for (int i4 = 0; i4 < 4; ++i4) { if (mt == 2 && i4 >= 2) continue;
;                 const int s = 2 * mt + (i4 >> 1), half = i4 & 1, ch0 = 16 * s + 8 * half + 4 * hh;
;                 const f32x4 ls2 = *(const LAS f32x4*)(par + 7 * LB + ch0);
;                 float A4[4], B4[4];
; #pragma unroll
;                 for (int q = 0; q < 4; ++q) { const int i = 4 * i4 + q;
;                     const float rg = rcpf_(1.0f + ex2(gr[i])), ig = rcpf_(1.0f + ex2(gi[i]));
;                     const float la2 = ls2[q] * rg, a = ex2(la2), xx = (2.0f * LN2) * la2;
;                     const float poly = -xx * (1.0f + xx * (0.5f + xx * ((1.0f / 6.0f) + xx * ((1.0f / 24.0f) + xx * (1.0f / 120.0f)))));
;                     const float om = (xx > -0.25f) ? poly : (1.0f - a * a);
;                     A4[q] = a; B4[q] = __builtin_amdgcn_sqrtf(om) * (ig * xc[s][half][q]); }
;                 asm volatile("s_nop 1\n\t"
;                     LRU_DPP4("row_shr:1 row_mask:0xf bank_mask:0xf") LRU_DPP4("row_shr:2 row_mask:0xf bank_mask:0xf") LRU_DPP4("row_shr:4 row_mask:0xf bank_mask:0xf")
;                     LRU_DPP4("row_shr:8 row_mask:0xf bank_mask:0xf") LRU_DPP4("row_bcast:15 row_mask:0xa bank_mask:0xf")
;                     : "+v"(A4[0]), "+v"(A4[1]), "+v"(A4[2]), "+v"(A4[3]), "+v"(B4[0]), "+v"(B4[1]), "+v"(B4[2]), "+v"(B4[3]));
; #pragma unroll
;                 for (int q = 0; q < 4; ++q) { Av[s][half][q] = A4[q]; xc[s][half][q] = B4[q]; }
;                 __builtin_amdgcn_sched_barrier(0); }
	ds_read_b128 v[0:3], v237 offset:6144
	ds_read_b128 v[140:143], v237 offset:7168
	ds_read_b128 v[16:19], v237 offset:24576
	ds_read_b128 v[144:147], v237 offset:25600
	s_waitcnt lgkmcnt(3)
	v_mfma_f32_32x32x16_bf16 v[0:15], v[0:3], v[36:39], 0
	s_waitcnt lgkmcnt(1)
	v_mfma_f32_32x32x16_bf16 v[16:31], v[16:19], v[36:39], 0
	v_mfma_f32_32x32x16_bf16 v[0:15], v[140:143], v[40:43], v[0:15]
	s_waitcnt lgkmcnt(0)
	v_mfma_f32_32x32x16_bf16 v[16:31], v[144:147], v[40:43], v[16:31]
	ds_read_b128 v[140:143], v237 offset:8192
	ds_read_b128 v[144:147], v237 offset:9216
	s_waitcnt lgkmcnt(1)
	v_mfma_f32_32x32x16_bf16 v[0:15], v[140:143], v[76:79], v[0:15]
	ds_read_b128 v[140:143], v237 offset:26624
	ds_read_b128 v[148:151], v237 offset:27648
	s_waitcnt lgkmcnt(1)
	v_mfma_f32_32x32x16_bf16 v[16:31], v[140:143], v[76:79], v[16:31]
	v_mfma_f32_32x32x16_bf16 v[0:15], v[144:147], v[112:115], v[0:15]
	ds_read_b128 v[140:143], v237 offset:10240
	ds_read_b128 v[144:147], v237 offset:11264
	s_waitcnt lgkmcnt(2)
	v_mfma_f32_32x32x16_bf16 v[16:31], v[148:151], v[112:115], v[16:31]
	s_waitcnt lgkmcnt(1)
	v_mfma_f32_32x32x16_bf16 v[0:15], v[140:143], v[124:127], v[0:15]
	ds_read_b128 v[140:143], v237 offset:28672
	ds_read_b128 v[148:151], v237 offset:29696
	s_waitcnt lgkmcnt(1)
	v_mfma_f32_32x32x16_bf16 v[16:31], v[140:143], v[124:127], v[16:31]
	v_mfma_f32_32x32x16_bf16 v[0:15], v[144:147], v[32:35], v[0:15]
	s_waitcnt lgkmcnt(0)
	v_mfma_f32_32x32x16_bf16 v[16:31], v[148:151], v[32:35], v[16:31]
	s_nop 9
	ds_read_b128 v[140:143], v234 offset:39232
	v_exp_f32_e32 v0, v0
	v_exp_f32_e32 v1, v1
	v_exp_f32_e32 v2, v2
	v_exp_f32_e32 v3, v3
	v_exp_f32_e32 v16, v16
	v_exp_f32_e32 v17, v17
	v_exp_f32_e32 v18, v18
	v_exp_f32_e32 v19, v19
	v_pk_add_f32 v[0:1], v[0:1], v[240:241] op_sel_hi:[1,0]
	v_pk_add_f32 v[2:3], v[2:3], v[240:241] op_sel_hi:[1,0]
	v_pk_add_f32 v[16:17], v[16:17], v[240:241] op_sel_hi:[1,0]
	v_pk_add_f32 v[18:19], v[18:19], v[240:241] op_sel_hi:[1,0]
	v_rcp_f32_e32 v0, v0
	v_rcp_f32_e32 v1, v1
	v_rcp_f32_e32 v2, v2
	v_rcp_f32_e32 v3, v3
	v_rcp_f32_e32 v16, v16
	v_rcp_f32_e32 v17, v17
	v_rcp_f32_e32 v18, v18
	v_rcp_f32_e32 v19, v19
	v_mul_f32_e32 v200, v81, v16
	v_mul_f32_e32 v201, v82, v17
	v_mul_f32_e32 v202, v86, v18
	v_mul_f32_e32 v203, v87, v19
	s_waitcnt lgkmcnt(0)
	v_pk_mul_f32 v[0:1], v[0:1], v[140:141]
	v_pk_mul_f32 v[2:3], v[2:3], v[142:143]
	v_pk_mul_f32 v[204:205], v[0:1], v[242:243] op_sel_hi:[1,0]
	v_pk_mul_f32 v[206:207], v[2:3], v[242:243] op_sel_hi:[1,0]
	v_exp_f32_e32 v80, v0
	v_exp_f32_e32 v81, v1
	v_exp_f32_e32 v82, v2
	v_exp_f32_e32 v83, v3
	v_pk_fma_f32 v[208:209], v[204:205], v[244:245], v[238:239] op_sel_hi:[1,0,0]
	v_pk_fma_f32 v[210:211], v[206:207], v[244:245], v[238:239] op_sel_hi:[1,0,0]
	v_pk_fma_f32 v[208:209], v[204:205], v[208:209], v[246:247] op_sel_hi:[1,1,0]
	v_pk_fma_f32 v[210:211], v[206:207], v[210:211], v[246:247] op_sel_hi:[1,1,0]
	v_pk_fma_f32 v[208:209], v[204:205], v[208:209], v[248:249] op_sel_hi:[1,1,0]
	v_pk_fma_f32 v[210:211], v[206:207], v[210:211], v[248:249] op_sel_hi:[1,1,0]
	v_pk_fma_f32 v[208:209], v[204:205], v[208:209], v[240:241] op_sel_hi:[1,1,0]
	v_pk_fma_f32 v[210:211], v[206:207], v[210:211], v[240:241] op_sel_hi:[1,1,0]
	v_pk_mul_f32 v[208:209], v[208:209], v[204:205] neg_lo:[0,1] neg_hi:[0,1]
	v_pk_mul_f32 v[210:211], v[210:211], v[206:207] neg_lo:[0,1] neg_hi:[0,1]
	v_pk_fma_f32 v[212:213], v[80:81], v[80:81], v[240:241] op_sel_hi:[1,1,0] neg_lo:[1,0,0] neg_hi:[1,0,0]
	v_pk_fma_f32 v[214:215], v[82:83], v[82:83], v[240:241] op_sel_hi:[1,1,0] neg_lo:[1,0,0] neg_hi:[1,0,0]
	v_cmp_lt_f32_e64 s[70:71], s29, v204
	v_cmp_lt_f32_e64 s[72:73], s29, v205
	v_cmp_lt_f32_e64 s[74:75], s29, v206
	v_cmp_lt_f32_e64 s[76:77], s29, v207
	v_cndmask_b32_e64 v212, v212, v208, s[70:71]
	v_cndmask_b32_e64 v213, v213, v209, s[72:73]
	v_cndmask_b32_e64 v214, v214, v210, s[74:75]
	v_cndmask_b32_e64 v215, v215, v211, s[76:77]
	v_sqrt_f32_e32 v212, v212
	v_sqrt_f32_e32 v213, v213
	v_sqrt_f32_e32 v214, v214
	v_sqrt_f32_e32 v215, v215
	v_pk_mul_f32 v[84:85], v[200:201], v[212:213]
	v_pk_mul_f32 v[86:87], v[202:203], v[214:215]
	s_nop 1
	v_fmac_f32_dpp v84, v84, v80 row_shr:1 row_mask:0xf bank_mask:0xf
	v_fmac_f32_dpp v85, v85, v81 row_shr:1 row_mask:0xf bank_mask:0xf
	v_fmac_f32_dpp v86, v86, v82 row_shr:1 row_mask:0xf bank_mask:0xf
	v_fmac_f32_dpp v87, v87, v83 row_shr:1 row_mask:0xf bank_mask:0xf
	v_mul_f32_dpp v80, v80, v80 row_shr:1 row_mask:0xf bank_mask:0xf
	v_mul_f32_dpp v81, v81, v81 row_shr:1 row_mask:0xf bank_mask:0xf
	v_mul_f32_dpp v82, v82, v82 row_shr:1 row_mask:0xf bank_mask:0xf
	v_mul_f32_dpp v83, v83, v83 row_shr:1 row_mask:0xf bank_mask:0xf
	v_fmac_f32_dpp v84, v84, v80 row_shr:2 row_mask:0xf bank_mask:0xf
	v_fmac_f32_dpp v85, v85, v81 row_shr:2 row_mask:0xf bank_mask:0xf
	v_fmac_f32_dpp v86, v86, v82 row_shr:2 row_mask:0xf bank_mask:0xf
	v_fmac_f32_dpp v87, v87, v83 row_shr:2 row_mask:0xf bank_mask:0xf
	v_mul_f32_dpp v80, v80, v80 row_shr:2 row_mask:0xf bank_mask:0xf
	v_mul_f32_dpp v81, v81, v81 row_shr:2 row_mask:0xf bank_mask:0xf
	v_mul_f32_dpp v82, v82, v82 row_shr:2 row_mask:0xf bank_mask:0xf
	v_mul_f32_dpp v83, v83, v83 row_shr:2 row_mask:0xf bank_mask:0xf
	v_fmac_f32_dpp v84, v84, v80 row_shr:4 row_mask:0xf bank_mask:0xf
	v_fmac_f32_dpp v85, v85, v81 row_shr:4 row_mask:0xf bank_mask:0xf
	v_fmac_f32_dpp v86, v86, v82 row_shr:4 row_mask:0xf bank_mask:0xf
	v_fmac_f32_dpp v87, v87, v83 row_shr:4 row_mask:0xf bank_mask:0xf
	v_mul_f32_dpp v80, v80, v80 row_shr:4 row_mask:0xf bank_mask:0xf
	v_mul_f32_dpp v81, v81, v81 row_shr:4 row_mask:0xf bank_mask:0xf
	v_mul_f32_dpp v82, v82, v82 row_shr:4 row_mask:0xf bank_mask:0xf
; #define LAS __attribute__((address_space(3)))
; __device__ __forceinline__ float ex2(float x) { return __builtin_amdgcn_exp2f(x); }
; __device__ __forceinline__ float rcpf_(float x) { return __builtin_amdgcn_rcpf(x); }
; __device__ __forceinline__ void lru_phase(const Ptrs& P, LAS unsigned char* lds, int G, int wave, int lane, int tid) {
;     ...
; #pragma unroll
;             for (int i4 = 0; i4 < 4; ++i4) { if (mt == 2 && i4 >= 2) continue;
;                 const int s = 2 * mt + (i4 >> 1), half = i4 & 1, ch0 = 16 * s + 8 * half + 4 * hh;
;                 const f32x4 ls2 = *(const LAS f32x4*)(par + 7 * LB + ch0);
;                 float A4[4], B4[4];
; #pragma unroll
;                 for (int q = 0; q < 4; ++q) { const int i = 4 * i4 + q;
;                     const float rg = rcpf_(1.0f + ex2(gr[i])), ig = rcpf_(1.0f + ex2(gi[i]));
;                     const float la2 = ls2[q] * rg, a = ex2(la2), xx = (2.0f * LN2) * la2;
;                     const float poly = -xx * (1.0f + xx * (0.5f + xx * ((1.0f / 6.0f) + xx * ((1.0f / 24.0f) + xx * (1.0f / 120.0f)))));
;                     const float om = (xx > -0.25f) ? poly : (1.0f - a * a);
;                     A4[q] = a; B4[q] = __builtin_amdgcn_sqrtf(om) * (ig * xc[s][half][q]); }
;                 asm volatile("s_nop 1\n\t"
;                     LRU_DPP4("row_shr:1 row_mask:0xf bank_mask:0xf") LRU_DPP4("row_shr:2 row_mask:0xf bank_mask:0xf") LRU_DPP4("row_shr:4 row_mask:0xf bank_mask:0xf")
;                     LRU_DPP4("row_shr:8 row_mask:0xf bank_mask:0xf") LRU_DPP4("row_bcast:15 row_mask:0xa bank_mask:0xf")
;                     : "+v"(A4[0]), "+v"(A4[1]), "+v"(A4[2]), "+v"(A4[3]), "+v"(B4[0]), "+v"(B4[1]), "+v"(B4[2]), "+v"(B4[3]));
; #pragma unroll
;                 for (int q = 0; q < 4; ++q) { Av[s][half][q] = A4[q]; xc[s][half][q] = B4[q]; }
;                 __builtin_amdgcn_sched_barrier(0); }
	v_mul_f32_dpp v83, v83, v83 row_shr:4 row_mask:0xf bank_mask:0xf
	v_fmac_f32_dpp v84, v84, v80 row_shr:8 row_mask:0xf bank_mask:0xf
	v_fmac_f32_dpp v85, v85, v81 row_shr:8 row_mask:0xf bank_mask:0xf
	v_fmac_f32_dpp v86, v86, v82 row_shr:8 row_mask:0xf bank_mask:0xf
	v_fmac_f32_dpp v87, v87, v83 row_shr:8 row_mask:0xf bank_mask:0xf
	v_mul_f32_dpp v80, v80, v80 row_shr:8 row_mask:0xf bank_mask:0xf
	v_mul_f32_dpp v81, v81, v81 row_shr:8 row_mask:0xf bank_mask:0xf
	v_mul_f32_dpp v82, v82, v82 row_shr:8 row_mask:0xf bank_mask:0xf
	v_mul_f32_dpp v83, v83, v83 row_shr:8 row_mask:0xf bank_mask:0xf
	v_fmac_f32_dpp v84, v84, v80 row_bcast:15 row_mask:0xa bank_mask:0xf
	v_fmac_f32_dpp v85, v85, v81 row_bcast:15 row_mask:0xa bank_mask:0xf
	v_fmac_f32_dpp v86, v86, v82 row_bcast:15 row_mask:0xa bank_mask:0xf
	v_fmac_f32_dpp v87, v87, v83 row_bcast:15 row_mask:0xa bank_mask:0xf
	v_mul_f32_dpp v80, v80, v80 row_bcast:15 row_mask:0xa bank_mask:0xf
	v_mul_f32_dpp v81, v81, v81 row_bcast:15 row_mask:0xa bank_mask:0xf
	v_mul_f32_dpp v82, v82, v82 row_bcast:15 row_mask:0xa bank_mask:0xf
	v_mul_f32_dpp v83, v83, v83 row_bcast:15 row_mask:0xa bank_mask:0xf
	ds_read_b128 v[0:3], v234 offset:39264
	v_exp_f32_e32 v4, v4
	v_exp_f32_e32 v5, v5
	v_exp_f32_e32 v6, v6
	v_exp_f32_e32 v7, v7
	v_exp_f32_e32 v20, v20
	v_exp_f32_e32 v21, v21
	v_exp_f32_e32 v22, v22
	v_exp_f32_e32 v23, v23
	v_pk_add_f32 v[4:5], v[4:5], v[240:241] op_sel_hi:[1,0]
	v_pk_add_f32 v[6:7], v[6:7], v[240:241] op_sel_hi:[1,0]
	v_pk_add_f32 v[20:21], v[20:21], v[240:241] op_sel_hi:[1,0]
	v_pk_add_f32 v[22:23], v[22:23], v[240:241] op_sel_hi:[1,0]
	v_rcp_f32_e32 v4, v4
	v_rcp_f32_e32 v5, v5
	v_rcp_f32_e32 v6, v6
	v_rcp_f32_e32 v7, v7
	v_rcp_f32_e32 v20, v20
	v_rcp_f32_e32 v21, v21
	v_rcp_f32_e32 v22, v22
	v_rcp_f32_e32 v23, v23
	v_mul_f32_e32 v200, v89, v20
	v_mul_f32_e32 v201, v90, v21
	v_mul_f32_e32 v202, v94, v22
	v_mul_f32_e32 v203, v95, v23
	s_waitcnt lgkmcnt(0)
	v_pk_mul_f32 v[4:5], v[4:5], v[0:1]
	v_pk_mul_f32 v[6:7], v[6:7], v[2:3]
	v_pk_mul_f32 v[204:205], v[4:5], v[242:243] op_sel_hi:[1,0]
	v_pk_mul_f32 v[206:207], v[6:7], v[242:243] op_sel_hi:[1,0]
	v_exp_f32_e32 v88, v4
	v_exp_f32_e32 v89, v5
	v_exp_f32_e32 v90, v6
	v_exp_f32_e32 v91, v7
	v_pk_fma_f32 v[208:209], v[204:205], v[244:245], v[238:239] op_sel_hi:[1,0,0]
	v_pk_fma_f32 v[210:211], v[206:207], v[244:245], v[238:239] op_sel_hi:[1,0,0]
	v_pk_fma_f32 v[208:209], v[204:205], v[208:209], v[246:247] op_sel_hi:[1,1,0]
	v_pk_fma_f32 v[210:211], v[206:207], v[210:211], v[246:247] op_sel_hi:[1,1,0]
	v_pk_fma_f32 v[208:209], v[204:205], v[208:209], v[248:249] op_sel_hi:[1,1,0]
	v_pk_fma_f32 v[210:211], v[206:207], v[210:211], v[248:249] op_sel_hi:[1,1,0]
	v_pk_fma_f32 v[208:209], v[204:205], v[208:209], v[240:241] op_sel_hi:[1,1,0]
	v_pk_fma_f32 v[210:211], v[206:207], v[210:211], v[240:241] op_sel_hi:[1,1,0]
	v_pk_mul_f32 v[208:209], v[208:209], v[204:205] neg_lo:[0,1] neg_hi:[0,1]
	v_pk_mul_f32 v[210:211], v[210:211], v[206:207] neg_lo:[0,1] neg_hi:[0,1]
	v_pk_fma_f32 v[212:213], v[88:89], v[88:89], v[240:241] op_sel_hi:[1,1,0] neg_lo:[1,0,0] neg_hi:[1,0,0]
	v_pk_fma_f32 v[214:215], v[90:91], v[90:91], v[240:241] op_sel_hi:[1,1,0] neg_lo:[1,0,0] neg_hi:[1,0,0]
	v_cmp_lt_f32_e64 s[70:71], s29, v204
	v_cmp_lt_f32_e64 s[72:73], s29, v205
	v_cmp_lt_f32_e64 s[74:75], s29, v206
	v_cmp_lt_f32_e64 s[76:77], s29, v207
	v_cndmask_b32_e64 v212, v212, v208, s[70:71]
	v_cndmask_b32_e64 v213, v213, v209, s[72:73]
	v_cndmask_b32_e64 v214, v214, v210, s[74:75]
	v_cndmask_b32_e64 v215, v215, v211, s[76:77]
	v_sqrt_f32_e32 v212, v212
	v_sqrt_f32_e32 v213, v213
	v_sqrt_f32_e32 v214, v214
	v_sqrt_f32_e32 v215, v215
	v_pk_mul_f32 v[92:93], v[200:201], v[212:213]
	v_pk_mul_f32 v[94:95], v[202:203], v[214:215]
	s_nop 1
	v_fmac_f32_dpp v92, v92, v88 row_shr:1 row_mask:0xf bank_mask:0xf
	v_fmac_f32_dpp v93, v93, v89 row_shr:1 row_mask:0xf bank_mask:0xf
	v_fmac_f32_dpp v94, v94, v90 row_shr:1 row_mask:0xf bank_mask:0xf
	v_fmac_f32_dpp v95, v95, v91 row_shr:1 row_mask:0xf bank_mask:0xf
	v_mul_f32_dpp v88, v88, v88 row_shr:1 row_mask:0xf bank_mask:0xf
	v_mul_f32_dpp v89, v89, v89 row_shr:1 row_mask:0xf bank_mask:0xf
	v_mul_f32_dpp v90, v90, v90 row_shr:1 row_mask:0xf bank_mask:0xf
	v_mul_f32_dpp v91, v91, v91 row_shr:1 row_mask:0xf bank_mask:0xf
	v_fmac_f32_dpp v92, v92, v88 row_shr:2 row_mask:0xf bank_mask:0xf
	v_fmac_f32_dpp v93, v93, v89 row_shr:2 row_mask:0xf bank_mask:0xf
	v_fmac_f32_dpp v94, v94, v90 row_shr:2 row_mask:0xf bank_mask:0xf
	v_fmac_f32_dpp v95, v95, v91 row_shr:2 row_mask:0xf bank_mask:0xf
	v_mul_f32_dpp v88, v88, v88 row_shr:2 row_mask:0xf bank_mask:0xf
	v_mul_f32_dpp v89, v89, v89 row_shr:2 row_mask:0xf bank_mask:0xf
	v_mul_f32_dpp v90, v90, v90 row_shr:2 row_mask:0xf bank_mask:0xf
	v_mul_f32_dpp v91, v91, v91 row_shr:2 row_mask:0xf bank_mask:0xf
	v_fmac_f32_dpp v92, v92, v88 row_shr:4 row_mask:0xf bank_mask:0xf
	v_fmac_f32_dpp v93, v93, v89 row_shr:4 row_mask:0xf bank_mask:0xf
	v_fmac_f32_dpp v94, v94, v90 row_shr:4 row_mask:0xf bank_mask:0xf
	v_fmac_f32_dpp v95, v95, v91 row_shr:4 row_mask:0xf bank_mask:0xf
	v_mul_f32_dpp v88, v88, v88 row_shr:4 row_mask:0xf bank_mask:0xf
	v_mul_f32_dpp v89, v89, v89 row_shr:4 row_mask:0xf bank_mask:0xf
	v_mul_f32_dpp v90, v90, v90 row_shr:4 row_mask:0xf bank_mask:0xf
	v_mul_f32_dpp v91, v91, v91 row_shr:4 row_mask:0xf bank_mask:0xf
	v_fmac_f32_dpp v92, v92, v88 row_shr:8 row_mask:0xf bank_mask:0xf
	v_fmac_f32_dpp v93, v93, v89 row_shr:8 row_mask:0xf bank_mask:0xf
	v_fmac_f32_dpp v94, v94, v90 row_shr:8 row_mask:0xf bank_mask:0xf
	v_fmac_f32_dpp v95, v95, v91 row_shr:8 row_mask:0xf bank_mask:0xf
; #define LAS __attribute__((address_space(3)))
; __device__ __forceinline__ float ex2(float x) { return __builtin_amdgcn_exp2f(x); }
; __device__ __forceinline__ float rcpf_(float x) { return __builtin_amdgcn_rcpf(x); }
; __device__ __forceinline__ void lru_phase(const Ptrs& P, LAS unsigned char* lds, int G, int wave, int lane, int tid) {
;     ...
; #pragma unroll
;             for (int i4 = 0; i4 < 4; ++i4) { if (mt == 2 && i4 >= 2) continue;
;                 const int s = 2 * mt + (i4 >> 1), half = i4 & 1, ch0 = 16 * s + 8 * half + 4 * hh;
;                 const f32x4 ls2 = *(const LAS f32x4*)(par + 7 * LB + ch0);
;                 float A4[4], B4[4];
; #pragma unroll
;                 for (int q = 0; q < 4; ++q) { const int i = 4 * i4 + q;
;                     const float rg = rcpf_(1.0f + ex2(gr[i])), ig = rcpf_(1.0f + ex2(gi[i]));
;                     const float la2 = ls2[q] * rg, a = ex2(la2), xx = (2.0f * LN2) * la2;
;                     const float poly = -xx * (1.0f + xx * (0.5f + xx * ((1.0f / 6.0f) + xx * ((1.0f / 24.0f) + xx * (1.0f / 120.0f)))));
;                     const float om = (xx > -0.25f) ? poly : (1.0f - a * a);
;                     A4[q] = a; B4[q] = __builtin_amdgcn_sqrtf(om) * (ig * xc[s][half][q]); }
;                 asm volatile("s_nop 1\n\t"
;                     LRU_DPP4("row_shr:1 row_mask:0xf bank_mask:0xf") LRU_DPP4("row_shr:2 row_mask:0xf bank_mask:0xf") LRU_DPP4("row_shr:4 row_mask:0xf bank_mask:0xf")
;                     LRU_DPP4("row_shr:8 row_mask:0xf bank_mask:0xf") LRU_DPP4("row_bcast:15 row_mask:0xa bank_mask:0xf")
;                     : "+v"(A4[0]), "+v"(A4[1]), "+v"(A4[2]), "+v"(A4[3]), "+v"(B4[0]), "+v"(B4[1]), "+v"(B4[2]), "+v"(B4[3]));
; #pragma unroll
;                 for (int q = 0; q < 4; ++q) { Av[s][half][q] = A4[q]; xc[s][half][q] = B4[q]; }
;                 __builtin_amdgcn_sched_barrier(0); }
	v_mul_f32_dpp v88, v88, v88 row_shr:8 row_mask:0xf bank_mask:0xf
	v_mul_f32_dpp v89, v89, v89 row_shr:8 row_mask:0xf bank_mask:0xf
	v_mul_f32_dpp v90, v90, v90 row_shr:8 row_mask:0xf bank_mask:0xf
	v_mul_f32_dpp v91, v91, v91 row_shr:8 row_mask:0xf bank_mask:0xf
	v_fmac_f32_dpp v92, v92, v88 row_bcast:15 row_mask:0xa bank_mask:0xf
	v_fmac_f32_dpp v93, v93, v89 row_bcast:15 row_mask:0xa bank_mask:0xf
	v_fmac_f32_dpp v94, v94, v90 row_bcast:15 row_mask:0xa bank_mask:0xf
	v_fmac_f32_dpp v95, v95, v91 row_bcast:15 row_mask:0xa bank_mask:0xf
	v_mul_f32_dpp v88, v88, v88 row_bcast:15 row_mask:0xa bank_mask:0xf
	v_mul_f32_dpp v89, v89, v89 row_bcast:15 row_mask:0xa bank_mask:0xf
	v_mul_f32_dpp v90, v90, v90 row_bcast:15 row_mask:0xa bank_mask:0xf
	v_mul_f32_dpp v91, v91, v91 row_bcast:15 row_mask:0xa bank_mask:0xf
	ds_read_b128 v[0:3], v234 offset:39296
	v_exp_f32_e32 v8, v8
	v_exp_f32_e32 v9, v9
	v_exp_f32_e32 v10, v10
	v_exp_f32_e32 v11, v11
	v_exp_f32_e32 v24, v24
	v_exp_f32_e32 v25, v25
	v_exp_f32_e32 v26, v26
	v_exp_f32_e32 v27, v27
	v_pk_add_f32 v[8:9], v[8:9], v[240:241] op_sel_hi:[1,0]
	v_pk_add_f32 v[10:11], v[10:11], v[240:241] op_sel_hi:[1,0]
	v_pk_add_f32 v[24:25], v[24:25], v[240:241] op_sel_hi:[1,0]
	v_pk_add_f32 v[26:27], v[26:27], v[240:241] op_sel_hi:[1,0]
	v_rcp_f32_e32 v8, v8
	v_rcp_f32_e32 v9, v9
	v_rcp_f32_e32 v10, v10
	v_rcp_f32_e32 v11, v11
	v_rcp_f32_e32 v24, v24
	v_rcp_f32_e32 v25, v25
	v_rcp_f32_e32 v26, v26
	v_rcp_f32_e32 v27, v27
	v_mul_f32_e32 v200, v97, v24
	v_mul_f32_e32 v201, v98, v25
	v_mul_f32_e32 v202, v102, v26
	v_mul_f32_e32 v203, v103, v27
	s_waitcnt lgkmcnt(0)
	v_pk_mul_f32 v[8:9], v[8:9], v[0:1]
	v_pk_mul_f32 v[10:11], v[10:11], v[2:3]
	v_pk_mul_f32 v[204:205], v[8:9], v[242:243] op_sel_hi:[1,0]
	v_pk_mul_f32 v[206:207], v[10:11], v[242:243] op_sel_hi:[1,0]
	v_exp_f32_e32 v96, v8
	v_exp_f32_e32 v97, v9
	v_exp_f32_e32 v98, v10
	v_exp_f32_e32 v99, v11
	v_pk_fma_f32 v[208:209], v[204:205], v[244:245], v[238:239] op_sel_hi:[1,0,0]
	v_pk_fma_f32 v[210:211], v[206:207], v[244:245], v[238:239] op_sel_hi:[1,0,0]
	v_pk_fma_f32 v[208:209], v[204:205], v[208:209], v[246:247] op_sel_hi:[1,1,0]
	v_pk_fma_f32 v[210:211], v[206:207], v[210:211], v[246:247] op_sel_hi:[1,1,0]
	v_pk_fma_f32 v[208:209], v[204:205], v[208:209], v[248:249] op_sel_hi:[1,1,0]
	v_pk_fma_f32 v[210:211], v[206:207], v[210:211], v[248:249] op_sel_hi:[1,1,0]
	v_pk_fma_f32 v[208:209], v[204:205], v[208:209], v[240:241] op_sel_hi:[1,1,0]
	v_pk_fma_f32 v[210:211], v[206:207], v[210:211], v[240:241] op_sel_hi:[1,1,0]
	v_pk_mul_f32 v[208:209], v[208:209], v[204:205] neg_lo:[0,1] neg_hi:[0,1]
	v_pk_mul_f32 v[210:211], v[210:211], v[206:207] neg_lo:[0,1] neg_hi:[0,1]
	v_pk_fma_f32 v[212:213], v[96:97], v[96:97], v[240:241] op_sel_hi:[1,1,0] neg_lo:[1,0,0] neg_hi:[1,0,0]
	v_pk_fma_f32 v[214:215], v[98:99], v[98:99], v[240:241] op_sel_hi:[1,1,0] neg_lo:[1,0,0] neg_hi:[1,0,0]
	v_cmp_lt_f32_e64 s[70:71], s29, v204
	v_cmp_lt_f32_e64 s[72:73], s29, v205
	v_cmp_lt_f32_e64 s[74:75], s29, v206
	v_cmp_lt_f32_e64 s[76:77], s29, v207
	v_cndmask_b32_e64 v212, v212, v208, s[70:71]
	v_cndmask_b32_e64 v213, v213, v209, s[72:73]
	v_cndmask_b32_e64 v214, v214, v210, s[74:75]
	v_cndmask_b32_e64 v215, v215, v211, s[76:77]
	v_sqrt_f32_e32 v212, v212
	v_sqrt_f32_e32 v213, v213
	v_sqrt_f32_e32 v214, v214
	v_sqrt_f32_e32 v215, v215
	v_pk_mul_f32 v[100:101], v[200:201], v[212:213]
	v_pk_mul_f32 v[102:103], v[202:203], v[214:215]
	s_nop 1
	v_fmac_f32_dpp v100, v100, v96 row_shr:1 row_mask:0xf bank_mask:0xf
	v_fmac_f32_dpp v101, v101, v97 row_shr:1 row_mask:0xf bank_mask:0xf
	v_fmac_f32_dpp v102, v102, v98 row_shr:1 row_mask:0xf bank_mask:0xf
	v_fmac_f32_dpp v103, v103, v99 row_shr:1 row_mask:0xf bank_mask:0xf
	v_mul_f32_dpp v96, v96, v96 row_shr:1 row_mask:0xf bank_mask:0xf
	v_mul_f32_dpp v97, v97, v97 row_shr:1 row_mask:0xf bank_mask:0xf
	v_mul_f32_dpp v98, v98, v98 row_shr:1 row_mask:0xf bank_mask:0xf
	v_mul_f32_dpp v99, v99, v99 row_shr:1 row_mask:0xf bank_mask:0xf
	v_fmac_f32_dpp v100, v100, v96 row_shr:2 row_mask:0xf bank_mask:0xf
	v_fmac_f32_dpp v101, v101, v97 row_shr:2 row_mask:0xf bank_mask:0xf
	v_fmac_f32_dpp v102, v102, v98 row_shr:2 row_mask:0xf bank_mask:0xf
	v_fmac_f32_dpp v103, v103, v99 row_shr:2 row_mask:0xf bank_mask:0xf
	v_mul_f32_dpp v96, v96, v96 row_shr:2 row_mask:0xf bank_mask:0xf
	v_mul_f32_dpp v97, v97, v97 row_shr:2 row_mask:0xf bank_mask:0xf
	v_mul_f32_dpp v98, v98, v98 row_shr:2 row_mask:0xf bank_mask:0xf
	v_mul_f32_dpp v99, v99, v99 row_shr:2 row_mask:0xf bank_mask:0xf
	v_fmac_f32_dpp v100, v100, v96 row_shr:4 row_mask:0xf bank_mask:0xf
	v_fmac_f32_dpp v101, v101, v97 row_shr:4 row_mask:0xf bank_mask:0xf
	v_fmac_f32_dpp v102, v102, v98 row_shr:4 row_mask:0xf bank_mask:0xf
	v_fmac_f32_dpp v103, v103, v99 row_shr:4 row_mask:0xf bank_mask:0xf
	v_mul_f32_dpp v96, v96, v96 row_shr:4 row_mask:0xf bank_mask:0xf
	v_mul_f32_dpp v97, v97, v97 row_shr:4 row_mask:0xf bank_mask:0xf
	v_mul_f32_dpp v98, v98, v98 row_shr:4 row_mask:0xf bank_mask:0xf
	v_mul_f32_dpp v99, v99, v99 row_shr:4 row_mask:0xf bank_mask:0xf
	v_fmac_f32_dpp v100, v100, v96 row_shr:8 row_mask:0xf bank_mask:0xf
	v_fmac_f32_dpp v101, v101, v97 row_shr:8 row_mask:0xf bank_mask:0xf
	v_fmac_f32_dpp v102, v102, v98 row_shr:8 row_mask:0xf bank_mask:0xf
	v_fmac_f32_dpp v103, v103, v99 row_shr:8 row_mask:0xf bank_mask:0xf
	v_mul_f32_dpp v96, v96, v96 row_shr:8 row_mask:0xf bank_mask:0xf
	v_mul_f32_dpp v97, v97, v97 row_shr:8 row_mask:0xf bank_mask:0xf
	v_mul_f32_dpp v98, v98, v98 row_shr:8 row_mask:0xf bank_mask:0xf
	v_mul_f32_dpp v99, v99, v99 row_shr:8 row_mask:0xf bank_mask:0xf
	v_fmac_f32_dpp v100, v100, v96 row_bcast:15 row_mask:0xa bank_mask:0xf
	v_fmac_f32_dpp v101, v101, v97 row_bcast:15 row_mask:0xa bank_mask:0xf
	v_fmac_f32_dpp v102, v102, v98 row_bcast:15 row_mask:0xa bank_mask:0xf
	v_fmac_f32_dpp v103, v103, v99 row_bcast:15 row_mask:0xa bank_mask:0xf
	v_mul_f32_dpp v96, v96, v96 row_bcast:15 row_mask:0xa bank_mask:0xf
	v_mul_f32_dpp v97, v97, v97 row_bcast:15 row_mask:0xa bank_mask:0xf
	v_mul_f32_dpp v98, v98, v98 row_bcast:15 row_mask:0xa bank_mask:0xf
	v_mul_f32_dpp v99, v99, v99 row_bcast:15 row_mask:0xa bank_mask:0xf
	ds_read_b128 v[0:3], v234 offset:39328
	v_exp_f32_e32 v12, v12
	v_exp_f32_e32 v13, v13
	v_exp_f32_e32 v14, v14
	v_exp_f32_e32 v15, v15
	v_exp_f32_e32 v28, v28
	v_exp_f32_e32 v29, v29
	v_exp_f32_e32 v30, v30
	v_exp_f32_e32 v31, v31
	v_pk_add_f32 v[12:13], v[12:13], v[240:241] op_sel_hi:[1,0]
	v_pk_add_f32 v[14:15], v[14:15], v[240:241] op_sel_hi:[1,0]
	v_pk_add_f32 v[28:29], v[28:29], v[240:241] op_sel_hi:[1,0]
	v_pk_add_f32 v[30:31], v[30:31], v[240:241] op_sel_hi:[1,0]
	v_rcp_f32_e32 v12, v12
	v_rcp_f32_e32 v13, v13
	v_rcp_f32_e32 v14, v14
	v_rcp_f32_e32 v15, v15
	v_rcp_f32_e32 v28, v28
	v_rcp_f32_e32 v29, v29
	v_rcp_f32_e32 v30, v30
	v_rcp_f32_e32 v31, v31
	v_mul_f32_e32 v200, v105, v28
	v_mul_f32_e32 v201, v106, v29
	v_mul_f32_e32 v202, v110, v30
	v_mul_f32_e32 v203, v111, v31
	s_waitcnt lgkmcnt(0)
; #define LAS __attribute__((address_space(3)))
; __device__ __forceinline__ float ex2(float x) { return __builtin_amdgcn_exp2f(x); }
; __device__ __forceinline__ float rcpf_(float x) { return __builtin_amdgcn_rcpf(x); }
; __device__ __forceinline__ void lru_phase(const Ptrs& P, LAS unsigned char* lds, int G, int wave, int lane, int tid) {
;     ...
; #pragma unroll
;             for (int i4 = 0; i4 < 4; ++i4) { if (mt == 2 && i4 >= 2) continue;
;                 const int s = 2 * mt + (i4 >> 1), half = i4 & 1, ch0 = 16 * s + 8 * half + 4 * hh;
;                 const f32x4 ls2 = *(const LAS f32x4*)(par + 7 * LB + ch0);
;                 float A4[4], B4[4];
; #pragma unroll
;                 for (int q = 0; q < 4; ++q) { const int i = 4 * i4 + q;
;                     const float rg = rcpf_(1.0f + ex2(gr[i])), ig = rcpf_(1.0f + ex2(gi[i]));
;                     const float la2 = ls2[q] * rg, a = ex2(la2), xx = (2.0f * LN2) * la2;
;                     const float poly = -xx * (1.0f + xx * (0.5f + xx * ((1.0f / 6.0f) + xx * ((1.0f / 24.0f) + xx * (1.0f / 120.0f)))));
;                     const float om = (xx > -0.25f) ? poly : (1.0f - a * a);
;                     A4[q] = a; B4[q] = __builtin_amdgcn_sqrtf(om) * (ig * xc[s][half][q]); }
;                 asm volatile("s_nop 1\n\t"
;                     LRU_DPP4("row_shr:1 row_mask:0xf bank_mask:0xf") LRU_DPP4("row_shr:2 row_mask:0xf bank_mask:0xf") LRU_DPP4("row_shr:4 row_mask:0xf bank_mask:0xf")
;                     LRU_DPP4("row_shr:8 row_mask:0xf bank_mask:0xf") LRU_DPP4("row_bcast:15 row_mask:0xa bank_mask:0xf")
;                     : "+v"(A4[0]), "+v"(A4[1]), "+v"(A4[2]), "+v"(A4[3]), "+v"(B4[0]), "+v"(B4[1]), "+v"(B4[2]), "+v"(B4[3]));
; #pragma unroll
;                 for (int q = 0; q < 4; ++q) { Av[s][half][q] = A4[q]; xc[s][half][q] = B4[q]; }
;                 __builtin_amdgcn_sched_barrier(0); }
	v_pk_mul_f32 v[12:13], v[12:13], v[0:1]
	v_pk_mul_f32 v[14:15], v[14:15], v[2:3]
	v_pk_mul_f32 v[204:205], v[12:13], v[242:243] op_sel_hi:[1,0]
	v_pk_mul_f32 v[206:207], v[14:15], v[242:243] op_sel_hi:[1,0]
	v_exp_f32_e32 v104, v12
	v_exp_f32_e32 v105, v13
	v_exp_f32_e32 v106, v14
	v_exp_f32_e32 v107, v15
	v_pk_fma_f32 v[208:209], v[204:205], v[244:245], v[238:239] op_sel_hi:[1,0,0]
	v_pk_fma_f32 v[210:211], v[206:207], v[244:245], v[238:239] op_sel_hi:[1,0,0]
	v_pk_fma_f32 v[208:209], v[204:205], v[208:209], v[246:247] op_sel_hi:[1,1,0]
	v_pk_fma_f32 v[210:211], v[206:207], v[210:211], v[246:247] op_sel_hi:[1,1,0]
	v_pk_fma_f32 v[208:209], v[204:205], v[208:209], v[248:249] op_sel_hi:[1,1,0]
	v_pk_fma_f32 v[210:211], v[206:207], v[210:211], v[248:249] op_sel_hi:[1,1,0]
	v_pk_fma_f32 v[208:209], v[204:205], v[208:209], v[240:241] op_sel_hi:[1,1,0]
	v_pk_fma_f32 v[210:211], v[206:207], v[210:211], v[240:241] op_sel_hi:[1,1,0]
	v_pk_mul_f32 v[208:209], v[208:209], v[204:205] neg_lo:[0,1] neg_hi:[0,1]
	v_pk_mul_f32 v[210:211], v[210:211], v[206:207] neg_lo:[0,1] neg_hi:[0,1]
	v_pk_fma_f32 v[212:213], v[104:105], v[104:105], v[240:241] op_sel_hi:[1,1,0] neg_lo:[1,0,0] neg_hi:[1,0,0]
	v_pk_fma_f32 v[214:215], v[106:107], v[106:107], v[240:241] op_sel_hi:[1,1,0] neg_lo:[1,0,0] neg_hi:[1,0,0]
	v_cmp_lt_f32_e64 s[70:71], s29, v204
	v_cmp_lt_f32_e64 s[72:73], s29, v205
	v_cmp_lt_f32_e64 s[74:75], s29, v206
	v_cmp_lt_f32_e64 s[76:77], s29, v207
	v_cndmask_b32_e64 v212, v212, v208, s[70:71]
	v_cndmask_b32_e64 v213, v213, v209, s[72:73]
	v_cndmask_b32_e64 v214, v214, v210, s[74:75]
	v_cndmask_b32_e64 v215, v215, v211, s[76:77]
	v_sqrt_f32_e32 v212, v212
	v_sqrt_f32_e32 v213, v213
	v_sqrt_f32_e32 v214, v214
	v_sqrt_f32_e32 v215, v215
	v_pk_mul_f32 v[108:109], v[200:201], v[212:213]
	v_pk_mul_f32 v[110:111], v[202:203], v[214:215]
	s_nop 1
	v_fmac_f32_dpp v108, v108, v104 row_shr:1 row_mask:0xf bank_mask:0xf
	v_fmac_f32_dpp v109, v109, v105 row_shr:1 row_mask:0xf bank_mask:0xf
	v_fmac_f32_dpp v110, v110, v106 row_shr:1 row_mask:0xf bank_mask:0xf
	v_fmac_f32_dpp v111, v111, v107 row_shr:1 row_mask:0xf bank_mask:0xf
	v_mul_f32_dpp v104, v104, v104 row_shr:1 row_mask:0xf bank_mask:0xf
	v_mul_f32_dpp v105, v105, v105 row_shr:1 row_mask:0xf bank_mask:0xf
	v_mul_f32_dpp v106, v106, v106 row_shr:1 row_mask:0xf bank_mask:0xf
	v_mul_f32_dpp v107, v107, v107 row_shr:1 row_mask:0xf bank_mask:0xf
	v_fmac_f32_dpp v108, v108, v104 row_shr:2 row_mask:0xf bank_mask:0xf
	v_fmac_f32_dpp v109, v109, v105 row_shr:2 row_mask:0xf bank_mask:0xf
	v_fmac_f32_dpp v110, v110, v106 row_shr:2 row_mask:0xf bank_mask:0xf
	v_fmac_f32_dpp v111, v111, v107 row_shr:2 row_mask:0xf bank_mask:0xf
	v_mul_f32_dpp v104, v104, v104 row_shr:2 row_mask:0xf bank_mask:0xf
	v_mul_f32_dpp v105, v105, v105 row_shr:2 row_mask:0xf bank_mask:0xf
	v_mul_f32_dpp v106, v106, v106 row_shr:2 row_mask:0xf bank_mask:0xf
	v_mul_f32_dpp v107, v107, v107 row_shr:2 row_mask:0xf bank_mask:0xf
	v_fmac_f32_dpp v108, v108, v104 row_shr:4 row_mask:0xf bank_mask:0xf
	v_fmac_f32_dpp v109, v109, v105 row_shr:4 row_mask:0xf bank_mask:0xf
	v_fmac_f32_dpp v110, v110, v106 row_shr:4 row_mask:0xf bank_mask:0xf
	v_fmac_f32_dpp v111, v111, v107 row_shr:4 row_mask:0xf bank_mask:0xf
	v_mul_f32_dpp v104, v104, v104 row_shr:4 row_mask:0xf bank_mask:0xf
	v_mul_f32_dpp v105, v105, v105 row_shr:4 row_mask:0xf bank_mask:0xf
	v_mul_f32_dpp v106, v106, v106 row_shr:4 row_mask:0xf bank_mask:0xf
	v_mul_f32_dpp v107, v107, v107 row_shr:4 row_mask:0xf bank_mask:0xf
	v_fmac_f32_dpp v108, v108, v104 row_shr:8 row_mask:0xf bank_mask:0xf
	v_fmac_f32_dpp v109, v109, v105 row_shr:8 row_mask:0xf bank_mask:0xf
	v_fmac_f32_dpp v110, v110, v106 row_shr:8 row_mask:0xf bank_mask:0xf
	v_fmac_f32_dpp v111, v111, v107 row_shr:8 row_mask:0xf bank_mask:0xf
	v_mul_f32_dpp v104, v104, v104 row_shr:8 row_mask:0xf bank_mask:0xf
	v_mul_f32_dpp v105, v105, v105 row_shr:8 row_mask:0xf bank_mask:0xf
	v_mul_f32_dpp v106, v106, v106 row_shr:8 row_mask:0xf bank_mask:0xf
	v_mul_f32_dpp v107, v107, v107 row_shr:8 row_mask:0xf bank_mask:0xf
	v_fmac_f32_dpp v108, v108, v104 row_bcast:15 row_mask:0xa bank_mask:0xf
	v_fmac_f32_dpp v109, v109, v105 row_bcast:15 row_mask:0xa bank_mask:0xf
	v_fmac_f32_dpp v110, v110, v106 row_bcast:15 row_mask:0xa bank_mask:0xf
	v_fmac_f32_dpp v111, v111, v107 row_bcast:15 row_mask:0xa bank_mask:0xf
	v_mul_f32_dpp v104, v104, v104 row_bcast:15 row_mask:0xa bank_mask:0xf
	v_mul_f32_dpp v105, v105, v105 row_bcast:15 row_mask:0xa bank_mask:0xf
	v_mul_f32_dpp v106, v106, v106 row_bcast:15 row_mask:0xa bank_mask:0xf
	v_mul_f32_dpp v107, v107, v107 row_bcast:15 row_mask:0xa bank_mask:0xf

; #define LAS __attribute__((address_space(3)))
; __device__ __forceinline__ void lru_phase(const Ptrs& P, LAS unsigned char* lds, int G, int wave, int lane, int tid) {
;     ...
;         for (int mt = 0; mt < 3; ++mt) {
;             f32x16 gr, gi;
; #pragma unroll
;             for (int i = 0; i < 16; ++i) { gr[i] = 0.f; gi[i] = 0.f; }
;             const LAS bf16x8* wa = (const LAS bf16x8*)(lds + L_WGF) + (size_t)(mt * 6) * 64 + lane;
;             const LAS bf16x8* wb = (const LAS bf16x8*)(lds + L_WGF) + (size_t)((3 + mt) * 6) * 64 + lane;
; #pragma unroll
;             for (int s = 0; s < 5; ++s) { gr = MFMA32(wa[s * 64], xf[s], gr); gi = MFMA32(wb[s * 64], xf[s], gi); }
;             gr = MFMA32(wa[5 * 64], xone, gr); gi = MFMA32(wb[5 * 64], xone, gi);
;             __builtin_amdgcn_sched_barrier(0);
; #pragma unroll
;             for (int i4 = 0; i4 < 4; ++i4) { if (mt == 2 && i4 >= 2) continue;
;                 const int s = 2 * mt + (i4 >> 1), half = i4 & 1, ch0 = 16 * s + 8 * half + 4 * hh;
;                 const f32x4 ls2 = *(const LAS f32x4*)(par + 7 * LB + ch0);
;                 float A4[4], B4[4];
; #pragma unroll
;                 for (int q = 0; q < 4; ++q) { const int i = 4 * i4 + q;
;                     const float rg = rcpf_(1.0f + ex2(gr[i])), ig = rcpf_(1.0f + ex2(gi[i]));
;                     const float la2 = ls2[q] * rg, a = ex2(la2), xx = (2.0f * LN2) * la2;
;                     const float poly = -xx * (1.0f + xx * (0.5f + xx * ((1.0f / 6.0f) + xx * ((1.0f / 24.0f) + xx * (1.0f / 120.0f)))));
;                     const float om = (xx > -0.25f) ? poly : (1.0f - a * a);
;                     A4[q] = a; B4[q] = __builtin_amdgcn_sqrtf(om) * (ig * xc[s][half][q]); }
;                 asm volatile("s_nop 1\n\t"
;                     LRU_DPP4("row_shr:1 row_mask:0xf bank_mask:0xf") LRU_DPP4("row_shr:2 row_mask:0xf bank_mask:0xf") LRU_DPP4("row_shr:4 row_mask:0xf bank_mask:0xf")
;                     LRU_DPP4("row_shr:8 row_mask:0xf bank_mask:0xf") LRU_DPP4("row_bcast:15 row_mask:0xa bank_mask:0xf")
;                     : "+v"(A4[0]), "+v"(A4[1]), "+v"(A4[2]), "+v"(A4[3]), "+v"(B4[0]), "+v"(B4[1]), "+v"(B4[2]), "+v"(B4[3]));
; #pragma unroll
;                 for (int q = 0; q < 4; ++q) { Av[s][half][q] = A4[q]; xc[s][half][q] = B4[q]; }
;                 __builtin_amdgcn_sched_barrier(0); }
	ds_read_b128 v[0:3], v237 offset:12288
	ds_read_b128 v[140:143], v237 offset:13312
	ds_read_b128 v[16:19], v237 offset:30720
	ds_read_b128 v[144:147], v237 offset:31744
	s_waitcnt lgkmcnt(3)
	v_mfma_f32_32x32x16_bf16 v[0:15], v[0:3], v[36:39], 0
	s_waitcnt lgkmcnt(1)
	v_mfma_f32_32x32x16_bf16 v[16:31], v[16:19], v[36:39], 0
	v_mfma_f32_32x32x16_bf16 v[0:15], v[140:143], v[40:43], v[0:15]
	s_waitcnt lgkmcnt(0)
	v_mfma_f32_32x32x16_bf16 v[16:31], v[144:147], v[40:43], v[16:31]
	ds_read_b128 v[36:39], v237 offset:14336
	ds_read_b128 v[40:43], v237 offset:15360
	s_waitcnt lgkmcnt(1)
	v_mfma_f32_32x32x16_bf16 v[0:15], v[36:39], v[76:79], v[0:15]
	ds_read_b128 v[36:39], v237 offset:32768
	ds_read_b128 v[140:143], v237 offset:33792
	s_waitcnt lgkmcnt(1)
	v_mfma_f32_32x32x16_bf16 v[16:31], v[36:39], v[76:79], v[16:31]
	v_mfma_f32_32x32x16_bf16 v[0:15], v[40:43], v[112:115], v[0:15]
	ds_read_b128 v[36:39], v237 offset:16384
	ds_read_b128 v[40:43], v237 offset:17408
	s_waitcnt lgkmcnt(2)
	v_mfma_f32_32x32x16_bf16 v[16:31], v[140:143], v[112:115], v[16:31]
	s_waitcnt lgkmcnt(1)
	v_mfma_f32_32x32x16_bf16 v[0:15], v[36:39], v[124:127], v[0:15]
	ds_read_b128 v[36:39], v237 offset:34816
	ds_read_b128 v[76:79], v237 offset:35840
	s_waitcnt lgkmcnt(1)
	v_mfma_f32_32x32x16_bf16 v[16:31], v[36:39], v[124:127], v[16:31]
	v_mfma_f32_32x32x16_bf16 v[0:15], v[40:43], v[32:35], v[0:15]
	s_waitcnt lgkmcnt(0)
	v_mfma_f32_32x32x16_bf16 v[16:31], v[76:79], v[32:35], v[16:31]
	s_nop 9
	ds_read_b128 v[8:11], v234 offset:39360
	v_exp_f32_e32 v0, v0
	v_exp_f32_e32 v1, v1
	v_exp_f32_e32 v2, v2
	v_exp_f32_e32 v3, v3
	v_exp_f32_e32 v16, v16
	v_exp_f32_e32 v17, v17
	v_exp_f32_e32 v18, v18
	v_exp_f32_e32 v19, v19
	v_pk_add_f32 v[0:1], v[0:1], v[240:241] op_sel_hi:[1,0]
	v_pk_add_f32 v[2:3], v[2:3], v[240:241] op_sel_hi:[1,0]
	v_pk_add_f32 v[16:17], v[16:17], v[240:241] op_sel_hi:[1,0]
	v_pk_add_f32 v[18:19], v[18:19], v[240:241] op_sel_hi:[1,0]
	v_rcp_f32_e32 v0, v0
	v_rcp_f32_e32 v1, v1
	v_rcp_f32_e32 v2, v2
	v_rcp_f32_e32 v3, v3
	v_rcp_f32_e32 v16, v16
	v_rcp_f32_e32 v17, v17
	v_rcp_f32_e32 v18, v18
	v_rcp_f32_e32 v19, v19
	v_mul_f32_e32 v200, v136, v16
	v_mul_f32_e32 v201, v129, v17
	v_mul_f32_e32 v202, v116, v18
	v_mul_f32_e32 v203, v119, v19
	s_waitcnt lgkmcnt(0)
	v_pk_mul_f32 v[0:1], v[0:1], v[8:9]
	v_pk_mul_f32 v[2:3], v[2:3], v[10:11]
	v_pk_mul_f32 v[204:205], v[0:1], v[242:243] op_sel_hi:[1,0]
	v_pk_mul_f32 v[206:207], v[2:3], v[242:243] op_sel_hi:[1,0]
	v_exp_f32_e32 v0, v0
	v_exp_f32_e32 v1, v1
	v_exp_f32_e32 v2, v2
	v_exp_f32_e32 v3, v3
	v_pk_fma_f32 v[208:209], v[204:205], v[244:245], v[238:239] op_sel_hi:[1,0,0]
	v_pk_fma_f32 v[210:211], v[206:207], v[244:245], v[238:239] op_sel_hi:[1,0,0]
	v_pk_fma_f32 v[208:209], v[204:205], v[208:209], v[246:247] op_sel_hi:[1,1,0]
	v_pk_fma_f32 v[210:211], v[206:207], v[210:211], v[246:247] op_sel_hi:[1,1,0]
	v_pk_fma_f32 v[208:209], v[204:205], v[208:209], v[248:249] op_sel_hi:[1,1,0]
	v_pk_fma_f32 v[210:211], v[206:207], v[210:211], v[248:249] op_sel_hi:[1,1,0]
	v_pk_fma_f32 v[208:209], v[204:205], v[208:209], v[240:241] op_sel_hi:[1,1,0]
	v_pk_fma_f32 v[210:211], v[206:207], v[210:211], v[240:241] op_sel_hi:[1,1,0]
	v_pk_mul_f32 v[208:209], v[208:209], v[204:205] neg_lo:[0,1] neg_hi:[0,1]
	v_pk_mul_f32 v[210:211], v[210:211], v[206:207] neg_lo:[0,1] neg_hi:[0,1]
	v_pk_fma_f32 v[212:213], v[0:1], v[0:1], v[240:241] op_sel_hi:[1,1,0] neg_lo:[1,0,0] neg_hi:[1,0,0]
	v_pk_fma_f32 v[214:215], v[2:3], v[2:3], v[240:241] op_sel_hi:[1,1,0] neg_lo:[1,0,0] neg_hi:[1,0,0]
	v_cmp_lt_f32_e64 s[70:71], s29, v204
	v_cmp_lt_f32_e64 s[72:73], s29, v205
	v_cmp_lt_f32_e64 s[74:75], s29, v206
	v_cmp_lt_f32_e64 s[76:77], s29, v207
	v_cndmask_b32_e64 v212, v212, v208, s[70:71]
	v_cndmask_b32_e64 v213, v213, v209, s[72:73]
	v_cndmask_b32_e64 v214, v214, v210, s[74:75]
	v_cndmask_b32_e64 v215, v215, v211, s[76:77]
	v_sqrt_f32_e32 v212, v212
	v_sqrt_f32_e32 v213, v213
	v_sqrt_f32_e32 v214, v214
	v_sqrt_f32_e32 v215, v215
	v_pk_mul_f32 v[8:9], v[200:201], v[212:213]
	v_pk_mul_f32 v[10:11], v[202:203], v[214:215]
	s_nop 1
	v_fmac_f32_dpp v8, v8, v0 row_shr:1 row_mask:0xf bank_mask:0xf
	v_fmac_f32_dpp v9, v9, v1 row_shr:1 row_mask:0xf bank_mask:0xf
	v_fmac_f32_dpp v10, v10, v2 row_shr:1 row_mask:0xf bank_mask:0xf
	v_fmac_f32_dpp v11, v11, v3 row_shr:1 row_mask:0xf bank_mask:0xf
	v_mul_f32_dpp v0, v0, v0 row_shr:1 row_mask:0xf bank_mask:0xf
	v_mul_f32_dpp v1, v1, v1 row_shr:1 row_mask:0xf bank_mask:0xf
	v_mul_f32_dpp v2, v2, v2 row_shr:1 row_mask:0xf bank_mask:0xf
	v_mul_f32_dpp v3, v3, v3 row_shr:1 row_mask:0xf bank_mask:0xf
	v_fmac_f32_dpp v8, v8, v0 row_shr:2 row_mask:0xf bank_mask:0xf
	v_fmac_f32_dpp v9, v9, v1 row_shr:2 row_mask:0xf bank_mask:0xf
	v_fmac_f32_dpp v10, v10, v2 row_shr:2 row_mask:0xf bank_mask:0xf
	v_fmac_f32_dpp v11, v11, v3 row_shr:2 row_mask:0xf bank_mask:0xf
	v_mul_f32_dpp v0, v0, v0 row_shr:2 row_mask:0xf bank_mask:0xf
	v_mul_f32_dpp v1, v1, v1 row_shr:2 row_mask:0xf bank_mask:0xf
	v_mul_f32_dpp v2, v2, v2 row_shr:2 row_mask:0xf bank_mask:0xf
	v_mul_f32_dpp v3, v3, v3 row_shr:2 row_mask:0xf bank_mask:0xf
	v_fmac_f32_dpp v8, v8, v0 row_shr:4 row_mask:0xf bank_mask:0xf
	v_fmac_f32_dpp v9, v9, v1 row_shr:4 row_mask:0xf bank_mask:0xf
	v_fmac_f32_dpp v10, v10, v2 row_shr:4 row_mask:0xf bank_mask:0xf
	v_fmac_f32_dpp v11, v11, v3 row_shr:4 row_mask:0xf bank_mask:0xf
	v_mul_f32_dpp v0, v0, v0 row_shr:4 row_mask:0xf bank_mask:0xf
	v_mul_f32_dpp v1, v1, v1 row_shr:4 row_mask:0xf bank_mask:0xf
	v_mul_f32_dpp v2, v2, v2 row_shr:4 row_mask:0xf bank_mask:0xf
	v_mul_f32_dpp v3, v3, v3 row_shr:4 row_mask:0xf bank_mask:0xf
; #define LAS __attribute__((address_space(3)))
; __device__ __forceinline__ float ex2(float x) { return __builtin_amdgcn_exp2f(x); }
; __device__ __forceinline__ float rcpf_(float x) { return __builtin_amdgcn_rcpf(x); }
; __device__ __forceinline__ void lru_phase(const Ptrs& P, LAS unsigned char* lds, int G, int wave, int lane, int tid) {
;     ...
; #pragma unroll
;             for (int i4 = 0; i4 < 4; ++i4) { if (mt == 2 && i4 >= 2) continue;
;                 const int s = 2 * mt + (i4 >> 1), half = i4 & 1, ch0 = 16 * s + 8 * half + 4 * hh;
;                 const f32x4 ls2 = *(const LAS f32x4*)(par + 7 * LB + ch0);
;                 float A4[4], B4[4];
; #pragma unroll
;                 for (int q = 0; q < 4; ++q) { const int i = 4 * i4 + q;
;                     const float rg = rcpf_(1.0f + ex2(gr[i])), ig = rcpf_(1.0f + ex2(gi[i]));
;                     const float la2 = ls2[q] * rg, a = ex2(la2), xx = (2.0f * LN2) * la2;
;                     const float poly = -xx * (1.0f + xx * (0.5f + xx * ((1.0f / 6.0f) + xx * ((1.0f / 24.0f) + xx * (1.0f / 120.0f)))));
;                     const float om = (xx > -0.25f) ? poly : (1.0f - a * a);
;                     A4[q] = a; B4[q] = __builtin_amdgcn_sqrtf(om) * (ig * xc[s][half][q]); }
;                 asm volatile("s_nop 1\n\t"
;                     LRU_DPP4("row_shr:1 row_mask:0xf bank_mask:0xf") LRU_DPP4("row_shr:2 row_mask:0xf bank_mask:0xf") LRU_DPP4("row_shr:4 row_mask:0xf bank_mask:0xf")
;                     LRU_DPP4("row_shr:8 row_mask:0xf bank_mask:0xf") LRU_DPP4("row_bcast:15 row_mask:0xa bank_mask:0xf")
;                     : "+v"(A4[0]), "+v"(A4[1]), "+v"(A4[2]), "+v"(A4[3]), "+v"(B4[0]), "+v"(B4[1]), "+v"(B4[2]), "+v"(B4[3]));
; #pragma unroll
;                 for (int q = 0; q < 4; ++q) { Av[s][half][q] = A4[q]; xc[s][half][q] = B4[q]; }
;                 __builtin_amdgcn_sched_barrier(0); }
	v_fmac_f32_dpp v8, v8, v0 row_shr:8 row_mask:0xf bank_mask:0xf
	v_fmac_f32_dpp v9, v9, v1 row_shr:8 row_mask:0xf bank_mask:0xf
	v_fmac_f32_dpp v10, v10, v2 row_shr:8 row_mask:0xf bank_mask:0xf
	v_fmac_f32_dpp v11, v11, v3 row_shr:8 row_mask:0xf bank_mask:0xf
	v_mul_f32_dpp v0, v0, v0 row_shr:8 row_mask:0xf bank_mask:0xf
	v_mul_f32_dpp v1, v1, v1 row_shr:8 row_mask:0xf bank_mask:0xf
	v_mul_f32_dpp v2, v2, v2 row_shr:8 row_mask:0xf bank_mask:0xf
	v_mul_f32_dpp v3, v3, v3 row_shr:8 row_mask:0xf bank_mask:0xf
	v_fmac_f32_dpp v8, v8, v0 row_bcast:15 row_mask:0xa bank_mask:0xf
	v_fmac_f32_dpp v9, v9, v1 row_bcast:15 row_mask:0xa bank_mask:0xf
	v_fmac_f32_dpp v10, v10, v2 row_bcast:15 row_mask:0xa bank_mask:0xf
	v_fmac_f32_dpp v11, v11, v3 row_bcast:15 row_mask:0xa bank_mask:0xf
	v_mul_f32_dpp v0, v0, v0 row_bcast:15 row_mask:0xa bank_mask:0xf
	v_mul_f32_dpp v1, v1, v1 row_bcast:15 row_mask:0xa bank_mask:0xf
	v_mul_f32_dpp v2, v2, v2 row_bcast:15 row_mask:0xa bank_mask:0xf
	v_mul_f32_dpp v3, v3, v3 row_bcast:15 row_mask:0xa bank_mask:0xf
	ds_read_b128 v[12:15], v234 offset:39392
	v_exp_f32_e32 v4, v4
	v_exp_f32_e32 v5, v5
	v_exp_f32_e32 v6, v6
	v_exp_f32_e32 v7, v7
	v_exp_f32_e32 v20, v20
	v_exp_f32_e32 v21, v21
	v_exp_f32_e32 v22, v22
	v_exp_f32_e32 v23, v23
	v_pk_add_f32 v[4:5], v[4:5], v[240:241] op_sel_hi:[1,0]
	v_pk_add_f32 v[6:7], v[6:7], v[240:241] op_sel_hi:[1,0]
	v_pk_add_f32 v[20:21], v[20:21], v[240:241] op_sel_hi:[1,0]
	v_pk_add_f32 v[22:23], v[22:23], v[240:241] op_sel_hi:[1,0]
	v_rcp_f32_e32 v4, v4
	v_rcp_f32_e32 v5, v5
	v_rcp_f32_e32 v6, v6
	v_rcp_f32_e32 v7, v7
	v_rcp_f32_e32 v20, v20
	v_rcp_f32_e32 v21, v21
	v_rcp_f32_e32 v22, v22
	v_rcp_f32_e32 v23, v23
	v_mul_f32_e32 v200, v120, v20
	v_mul_f32_e32 v201, v118, v21
	v_mul_f32_e32 v202, v117, v22
	v_mul_f32_e32 v203, v123, v23
	s_waitcnt lgkmcnt(0)
	v_pk_mul_f32 v[4:5], v[4:5], v[12:13]
	v_pk_mul_f32 v[6:7], v[6:7], v[14:15]
	v_pk_mul_f32 v[204:205], v[4:5], v[242:243] op_sel_hi:[1,0]
	v_pk_mul_f32 v[206:207], v[6:7], v[242:243] op_sel_hi:[1,0]
	v_exp_f32_e32 v4, v4
	v_exp_f32_e32 v5, v5
	v_exp_f32_e32 v6, v6
	v_exp_f32_e32 v7, v7
	v_pk_fma_f32 v[208:209], v[204:205], v[244:245], v[238:239] op_sel_hi:[1,0,0]
	v_pk_fma_f32 v[210:211], v[206:207], v[244:245], v[238:239] op_sel_hi:[1,0,0]
	v_pk_fma_f32 v[208:209], v[204:205], v[208:209], v[246:247] op_sel_hi:[1,1,0]
	v_pk_fma_f32 v[210:211], v[206:207], v[210:211], v[246:247] op_sel_hi:[1,1,0]
	v_pk_fma_f32 v[208:209], v[204:205], v[208:209], v[248:249] op_sel_hi:[1,1,0]
	v_pk_fma_f32 v[210:211], v[206:207], v[210:211], v[248:249] op_sel_hi:[1,1,0]
	v_pk_fma_f32 v[208:209], v[204:205], v[208:209], v[240:241] op_sel_hi:[1,1,0]
	v_pk_fma_f32 v[210:211], v[206:207], v[210:211], v[240:241] op_sel_hi:[1,1,0]
	v_pk_mul_f32 v[208:209], v[208:209], v[204:205] neg_lo:[0,1] neg_hi:[0,1]
	v_pk_mul_f32 v[210:211], v[210:211], v[206:207] neg_lo:[0,1] neg_hi:[0,1]
	v_pk_fma_f32 v[212:213], v[4:5], v[4:5], v[240:241] op_sel_hi:[1,1,0] neg_lo:[1,0,0] neg_hi:[1,0,0]
	v_pk_fma_f32 v[214:215], v[6:7], v[6:7], v[240:241] op_sel_hi:[1,1,0] neg_lo:[1,0,0] neg_hi:[1,0,0]
	v_cmp_lt_f32_e64 s[70:71], s29, v204
	v_cmp_lt_f32_e64 s[72:73], s29, v205
	v_cmp_lt_f32_e64 s[74:75], s29, v206
	v_cmp_lt_f32_e64 s[76:77], s29, v207
	v_cndmask_b32_e64 v212, v212, v208, s[70:71]
	v_cndmask_b32_e64 v213, v213, v209, s[72:73]
	v_cndmask_b32_e64 v214, v214, v210, s[74:75]
	v_cndmask_b32_e64 v215, v215, v211, s[76:77]
	v_sqrt_f32_e32 v212, v212
	v_sqrt_f32_e32 v213, v213
	v_sqrt_f32_e32 v214, v214
	v_sqrt_f32_e32 v215, v215
	v_pk_mul_f32 v[12:13], v[200:201], v[212:213]
	v_pk_mul_f32 v[14:15], v[202:203], v[214:215]
	s_nop 1
	v_fmac_f32_dpp v12, v12, v4 row_shr:1 row_mask:0xf bank_mask:0xf
	v_fmac_f32_dpp v13, v13, v5 row_shr:1 row_mask:0xf bank_mask:0xf
	v_fmac_f32_dpp v14, v14, v6 row_shr:1 row_mask:0xf bank_mask:0xf
	v_fmac_f32_dpp v15, v15, v7 row_shr:1 row_mask:0xf bank_mask:0xf
	v_mul_f32_dpp v4, v4, v4 row_shr:1 row_mask:0xf bank_mask:0xf
	v_mul_f32_dpp v5, v5, v5 row_shr:1 row_mask:0xf bank_mask:0xf
	v_mul_f32_dpp v6, v6, v6 row_shr:1 row_mask:0xf bank_mask:0xf
	v_mul_f32_dpp v7, v7, v7 row_shr:1 row_mask:0xf bank_mask:0xf
	v_fmac_f32_dpp v12, v12, v4 row_shr:2 row_mask:0xf bank_mask:0xf
	v_fmac_f32_dpp v13, v13, v5 row_shr:2 row_mask:0xf bank_mask:0xf
	v_fmac_f32_dpp v14, v14, v6 row_shr:2 row_mask:0xf bank_mask:0xf
	v_fmac_f32_dpp v15, v15, v7 row_shr:2 row_mask:0xf bank_mask:0xf
	v_mul_f32_dpp v4, v4, v4 row_shr:2 row_mask:0xf bank_mask:0xf
	v_mul_f32_dpp v5, v5, v5 row_shr:2 row_mask:0xf bank_mask:0xf
	v_mul_f32_dpp v6, v6, v6 row_shr:2 row_mask:0xf bank_mask:0xf
	v_mul_f32_dpp v7, v7, v7 row_shr:2 row_mask:0xf bank_mask:0xf
	v_fmac_f32_dpp v12, v12, v4 row_shr:4 row_mask:0xf bank_mask:0xf
	v_fmac_f32_dpp v13, v13, v5 row_shr:4 row_mask:0xf bank_mask:0xf
	v_fmac_f32_dpp v14, v14, v6 row_shr:4 row_mask:0xf bank_mask:0xf
	v_fmac_f32_dpp v15, v15, v7 row_shr:4 row_mask:0xf bank_mask:0xf
	v_mul_f32_dpp v4, v4, v4 row_shr:4 row_mask:0xf bank_mask:0xf
	v_mul_f32_dpp v5, v5, v5 row_shr:4 row_mask:0xf bank_mask:0xf
	v_mul_f32_dpp v6, v6, v6 row_shr:4 row_mask:0xf bank_mask:0xf
	v_mul_f32_dpp v7, v7, v7 row_shr:4 row_mask:0xf bank_mask:0xf
	v_fmac_f32_dpp v12, v12, v4 row_shr:8 row_mask:0xf bank_mask:0xf
	v_fmac_f32_dpp v13, v13, v5 row_shr:8 row_mask:0xf bank_mask:0xf
	v_fmac_f32_dpp v14, v14, v6 row_shr:8 row_mask:0xf bank_mask:0xf
	v_fmac_f32_dpp v15, v15, v7 row_shr:8 row_mask:0xf bank_mask:0xf
	v_mul_f32_dpp v4, v4, v4 row_shr:8 row_mask:0xf bank_mask:0xf
	v_mul_f32_dpp v5, v5, v5 row_shr:8 row_mask:0xf bank_mask:0xf
	v_mul_f32_dpp v6, v6, v6 row_shr:8 row_mask:0xf bank_mask:0xf
	v_mul_f32_dpp v7, v7, v7 row_shr:8 row_mask:0xf bank_mask:0xf
	v_fmac_f32_dpp v12, v12, v4 row_bcast:15 row_mask:0xa bank_mask:0xf
	v_fmac_f32_dpp v13, v13, v5 row_bcast:15 row_mask:0xa bank_mask:0xf
	v_fmac_f32_dpp v14, v14, v6 row_bcast:15 row_mask:0xa bank_mask:0xf
	v_fmac_f32_dpp v15, v15, v7 row_bcast:15 row_mask:0xa bank_mask:0xf
	v_mul_f32_dpp v4, v4, v4 row_bcast:15 row_mask:0xa bank_mask:0xf
	v_mul_f32_dpp v5, v5, v5 row_bcast:15 row_mask:0xa bank_mask:0xf
	v_mul_f32_dpp v6, v6, v6 row_bcast:15 row_mask:0xa bank_mask:0xf
	v_mul_f32_dpp v7, v7, v7 row_bcast:15 row_mask:0xa bank_mask:0xf

; #define LAS __attribute__((address_space(3)))
; __device__ __forceinline__ void lru_phase(const Ptrs& P, LAS unsigned char* lds, int G, int wave, int lane, int tid) {
;     ...
;         { const bf16* gp = U0 + (size_t)M * LW + ((size_t)(((b * 128 + (tloc >> 5)) * 16 + hd) * 10) * 64 + lane) * 4;
; #pragma unroll
;           for (int gq = 0; gq < 10; ++gq) graw_[gq] = *(const v2u*)(gp + gq * 256); }
;         if (r == 31) { LAS float* cp = (LAS float*)(lds + L_COMP) + wave * 160 + 4 * hh;
; #pragma unroll
;             for (int s = 0; s < 5; ++s)
; #pragma unroll
;                 for (int half = 0; half < 2; ++half) { const int ch0 = 16 * s + 8 * half;
;                     *(LAS f32x4*)(cp + ch0) = (f32x4){Av[s][half][0], Av[s][half][1], Av[s][half][2], Av[s][half][3]};
;                     *(LAS f32x4*)(cp + 80 + ch0) = (f32x4){xc[s][half][0], xc[s][half][1], xc[s][half][2], xc[s][half][3]}; } }
	s_lshl_b32 s6, s31, 11
	s_lshr_b32 s7, s34, 1
	s_and_b32 s37, s20, 15
	s_add_i32 s7, s7, s6
	s_or_b32 s6, s7, s37
	s_mul_i32 s6, s6, 10
	s_ashr_i32 s7, s6, 31
	s_lshl_b64 s[6:7], s[6:7], 9
	v_lshl_add_u64 v[16:17], v[130:131], 0, s[6:7]
	global_load_dwordx2 v[200:201], v[16:17], off
	global_load_dwordx2 v[196:197], v[16:17], off offset:512
	global_load_dwordx2 v[194:195], v[16:17], off offset:1024
	global_load_dwordx2 v[192:193], v[16:17], off offset:1536
	global_load_dwordx2 v[190:191], v[16:17], off offset:2048
	global_load_dwordx2 v[188:189], v[16:17], off offset:2560
	global_load_dwordx2 v[182:183], v[16:17], off offset:3072
	global_load_dwordx2 v[180:181], v[16:17], off offset:3584
	v_add_co_u32_e32 v16, vcc, 0x1000, v16
	s_nop 1
	v_addc_co_u32_e32 v17, vcc, 0, v17, vcc
	global_load_dwordx2 v[178:179], v[16:17], off
	global_load_dwordx2 v[176:177], v[16:17], off offset:512
	s_and_saveexec_b64 s[6:7], s[2:3]
	s_cbranch_execz .LBB0_310
	v_add_u32_e32 v16, s27, v233
	ds_write_b128 v16, v[44:47] offset:39424
	ds_write_b128 v16, v[48:51] offset:39744
	ds_write_b128 v16, v[52:55] offset:39456
	ds_write_b128 v16, v[56:59] offset:39776
	ds_write_b128 v16, v[60:63] offset:39488
	ds_write_b128 v16, v[64:67] offset:39808
	ds_write_b128 v16, v[68:71] offset:39520
	ds_write_b128 v16, v[72:75] offset:39840
	ds_write_b128 v16, v[80:83] offset:39552
	ds_write_b128 v16, v[84:87] offset:39872
	ds_write_b128 v16, v[88:91] offset:39584
	ds_write_b128 v16, v[92:95] offset:39904
	ds_write_b128 v16, v[96:99] offset:39616
	ds_write_b128 v16, v[100:103] offset:39936
	ds_write_b128 v16, v[104:107] offset:39648
	ds_write_b128 v16, v[108:111] offset:39968
	ds_write_b128 v16, v[0:3] offset:39680
	ds_write_b128 v16, v[8:11] offset:40000
	ds_write_b128 v16, v[4:7] offset:39712
	ds_write_b128 v16, v[12:15] offset:40032
